# seam-hosted weight converters store with plain write-back stores instead of nt (nt stores take the slow path and head the next phase's in-order vmcnt queue)
# speedup vs baseline: 1.0024x; 1.0024x over previous
; #define LAS __attribute__((address_space(3)))
; #define TR_LOAD(p) __builtin_nontemporal_load(p)
; __device__ __forceinline__ TrItem tr_decode(int it, const float* const* in, unsigned char* ws, int lane) {
;     ...
;     else if ((r -= 1024) < 5632) { kind = 1; W = in[17]; W2 = in[18]; N = FF; ndb = 176; gain = in[16]; WT = (bf16_t*)(ws + WS_W2GU); nts = true; }
;     else { r -= 5632; W = in[19]; K = FF; WT = (bf16_t*)(ws + WS_W2D); }
;     ...
;     constexpr int KL = TR_ORDER, DL = 3 - TR_ORDER;
;     const int rh = r >> 3, rl = r & 7, nq = ndb >> DL, kbh = rh / nq, dbh = rh - kbh * nq;
;     const int kb = (kbh << KL) + (rl >> DL), db = (dbh << DL) + (rl & ((1 << DL) - 1)), d0 = db * 64, k0 = kb * 64;
;     ...
;     const int kb = r / ndb, db = r - kb * ndb, d0 = db * 64, k0 = kb * 64;
;     ...
;     const int blk = d0 + 32 * ((lane & 15) >> 3);
;     const float* src = W; int s0 = blk;
;     if (kind == 1) { const int pn = blk >> 8, bj = (blk >> 7) & 1, o = blk & 127; src = bj ? W2 : W; s0 = pn * 128 + o; }
;     else if (kind == 2) s0 = win_src(blk);
;     TrItem t; t.src = src + (size_t)(k0 + (lane >> 4)) * N + s0 + 4 * (lane & 7); t.gain = gain ? gain + k0 + 8 * (lane & 7) : nullptr;
;     t.dst = WT + (size_t)(d0 + (lane >> 3)) * K + k0 + 8 * (lane & 7); t.N = N; t.K = K; t.nts = nts && TR_NTS;
;     if (woh) { t.dst = WT + ((size_t)((k0 >> 9) * 2048 + d0 + (lane >> 3))) * 512 + (k0 & 511) + 8 * (lane & 7); t.K = 512; }
;     return t;
; }
;     __device__ __forceinline__ int count() const { return (e0 - b0) + (e1 - b1) + (e2 - b2); }
; __device__ __forceinline__ void tr_all(const float* const* in, unsigned char* ws, LAS float* scr, int gw, int ngw, int lane, const TrRanges rg) {
;     const int TR_CNT = rg.count();
;     if (gw >= TR_CNT) return;
;     TrItem cur = tr_decode(rg.item(gw), in, ws, lane);
;     f32x4 v[16];
; #pragma unroll
;     for (int i = 0; i < 16; ++i) v[i] = TR_LOAD((const f32x4*)(cur.src + (size_t)(4 * i) * cur.N));
;     for (int it = gw; it < TR_CNT; it += ngw) {
;         const int nit = it + ngw; const bool hn = nit < TR_CNT;
;         TrItem nx = cur; f32x4 w[16];
;         if (hn) { nx = tr_decode(rg.item(nit), in, ws, lane);
; #pragma unroll
;             for (int i = 0; i < 16; ++i) w[i] = TR_LOAD((const f32x4*)(nx.src + (size_t)(4 * i) * nx.N)); }
;         LAS float* wp = scr + (lane >> 4) * 65 + 4 * (lane & 15);
; #pragma unroll
.Lseam_cv_0:
	s_cmp_lt_u32 s98, 2
	s_cbranch_scc1 .LBB0_339
	s_cmp_gt_u32 s98, 5
	s_cbranch_scc1 .Lseam_cv_0_1
	s_mov_b64 exec, -1
	s_lshl_b32 s99, s87, 2
	s_add_i32 s99, s99, s98
	s_add_i32 s99, s99, 0x5fe
	s_lshr_b32 s100, s99, 3
	s_mul_i32 s101, s100, 0x5d2
	s_lshr_b32 s101, s101, 16
	s_mul_i32 vcc_lo, s101, 44
	s_sub_i32 s100, s100, vcc_lo
	s_and_b32 vcc_lo, s99, 7
	s_lshr_b32 vcc_hi, vcc_lo, 2
	s_lshl_b32 s101, s101, 1
	s_add_i32 s101, s101, vcc_hi
	s_and_b32 vcc_lo, vcc_lo, 3
	s_lshl_b32 s100, s100, 2
	s_add_i32 s100, s100, vcc_lo
	s_lshl_b32 s101, s101, 6
	s_lshl_b32 s100, s100, 6
	v_and_b32_e32 v66, 63, v1
	v_lshrrev_b32_e32 v67, 4, v66
	v_and_b32_e32 v68, 15, v66
	v_and_b32_e32 v73, 7, v66
	v_lshrrev_b32_e32 v72, 3, v66
	s_mul_i32 s99, s98, 0x4100
	v_mul_u32_u24_e32 v70, 0x104, v67
	v_lshl_add_u32 v70, v68, 4, v70
	v_add_u32_e32 v70, s99, v70
	v_mul_u32_u24_e32 v71, 0x820, v73
	v_lshl_add_u32 v71, v72, 2, v71
	v_add_u32_e32 v71, s99, v71
	s_mul_i32 s99, s101, 0x1600
	s_lshr_b32 vcc_lo, s100, 8
	s_lshl_b32 vcc_lo, vcc_lo, 7
	s_add_i32 s99, s99, vcc_lo
	s_and_b32 vcc_lo, s100, 0x7f
	s_add_i32 s99, s99, vcc_lo
	s_lshl_b32 s99, s99, 2
	v_mul_u32_u24_e32 v69, 0x5800, v67
	v_lshl_add_u32 v69, v68, 4, v69
	v_add_u32_e32 v69, s99, v69
	s_lshl_b32 s99, s100, 12
	s_lshl_b32 vcc_lo, s101, 1
	s_add_i32 s99, s99, vcc_lo
	v_lshlrev_b32_e32 v72, 12, v72
	v_lshl_add_u32 v72, v73, 4, v72
	v_add_u32_e32 v72, s99, v72
	s_lshl_b32 s99, s101, 2
	v_lshlrev_b32_e32 v73, 5, v73
	v_add_u32_e32 v73, s99, v73
	s_nop 0
	s_bitcmp1_b32 s100, 7
	v_readlane_b32 s100, v254, 6
	v_readlane_b32 s101, v254, 7
	v_readlane_b32 s98, v254, 8
	v_readlane_b32 s99, v254, 9
	s_nop 3
	s_cselect_b32 s100, s98, s100
	s_cselect_b32 s101, s99, s101
	v_readlane_b32 s98, v254, 4
	v_readlane_b32 s99, v254, 5
	global_load_dwordx4 v[2:5], v69, s[100:101] nt
	v_add_u32_e32 v68, 0x16000, v69
	global_load_dwordx4 v[6:9], v68, s[100:101] nt
	v_add_u32_e32 v67, 0x2c000, v69
	global_load_dwordx4 v[10:13], v67, s[100:101] nt
	v_add_u32_e32 v68, 0x42000, v69
	global_load_dwordx4 v[14:17], v68, s[100:101] nt
	v_add_u32_e32 v67, 0x58000, v69
	global_load_dwordx4 v[18:21], v67, s[100:101] nt
	v_add_u32_e32 v68, 0x6e000, v69
	global_load_dwordx4 v[22:25], v68, s[100:101] nt
	v_add_u32_e32 v67, 0x84000, v69
	global_load_dwordx4 v[26:29], v67, s[100:101] nt
	v_add_u32_e32 v68, 0x9a000, v69
	global_load_dwordx4 v[30:33], v68, s[100:101] nt
	v_add_u32_e32 v67, 0xb0000, v69
	global_load_dwordx4 v[34:37], v67, s[100:101] nt
	v_add_u32_e32 v68, 0xc6000, v69
	global_load_dwordx4 v[38:41], v68, s[100:101] nt
	v_add_u32_e32 v67, 0xdc000, v69
	global_load_dwordx4 v[42:45], v67, s[100:101] nt
	v_add_u32_e32 v68, 0xf2000, v69
	global_load_dwordx4 v[46:49], v68, s[100:101] nt
	v_add_u32_e32 v67, 0x108000, v69
	global_load_dwordx4 v[50:53], v67, s[100:101] nt
	v_add_u32_e32 v68, 0x11e000, v69
	global_load_dwordx4 v[54:57], v68, s[100:101] nt
	v_add_u32_e32 v67, 0x134000, v69
	global_load_dwordx4 v[58:61], v67, s[100:101] nt
	v_add_u32_e32 v68, 0x14a000, v69
	global_load_dwordx4 v[62:65], v68, s[100:101] nt
	global_load_dwordx4 v[74:77], v73, s[98:99]
	global_load_dwordx4 v[78:81], v73, s[98:99] offset:16
	s_waitcnt vmcnt(17)
	ds_write_b32 v70, v2
	ds_write_b32 v70, v3 offset:4
	ds_write_b32 v70, v4 offset:8
	ds_write_b32 v70, v5 offset:12
	s_waitcnt vmcnt(16)
	ds_write_b32 v70, v6 offset:1040
	ds_write_b32 v70, v7 offset:1044
	ds_write_b32 v70, v8 offset:1048
	ds_write_b32 v70, v9 offset:1052
	s_waitcnt vmcnt(15)
	ds_write_b32 v70, v10 offset:2080
	ds_write_b32 v70, v11 offset:2084
	ds_write_b32 v70, v12 offset:2088
	ds_write_b32 v70, v13 offset:2092
	s_waitcnt vmcnt(14)
	ds_write_b32 v70, v14 offset:3120
	ds_write_b32 v70, v15 offset:3124
	ds_write_b32 v70, v16 offset:3128
	ds_write_b32 v70, v17 offset:3132
	s_waitcnt vmcnt(13)
	ds_write_b32 v70, v18 offset:4160
	ds_write_b32 v70, v19 offset:4164
	ds_write_b32 v70, v20 offset:4168
	ds_write_b32 v70, v21 offset:4172
	s_waitcnt vmcnt(12)
	ds_write_b32 v70, v22 offset:5200
	ds_write_b32 v70, v23 offset:5204
	ds_write_b32 v70, v24 offset:5208
	ds_write_b32 v70, v25 offset:5212
	s_waitcnt vmcnt(11)
	ds_write_b32 v70, v26 offset:6240
	ds_write_b32 v70, v27 offset:6244
	ds_write_b32 v70, v28 offset:6248
	ds_write_b32 v70, v29 offset:6252
	s_waitcnt vmcnt(10)
	ds_write_b32 v70, v30 offset:7280
	ds_write_b32 v70, v31 offset:7284
	ds_write_b32 v70, v32 offset:7288
	ds_write_b32 v70, v33 offset:7292
	s_waitcnt vmcnt(9)
	ds_write_b32 v70, v34 offset:8320
	ds_write_b32 v70, v35 offset:8324
	ds_write_b32 v70, v36 offset:8328
	ds_write_b32 v70, v37 offset:8332
	s_waitcnt vmcnt(8)
	ds_write_b32 v70, v38 offset:9360
	ds_write_b32 v70, v39 offset:9364
	ds_write_b32 v70, v40 offset:9368
	ds_write_b32 v70, v41 offset:9372
	s_waitcnt vmcnt(7)
	ds_write_b32 v70, v42 offset:10400
	ds_write_b32 v70, v43 offset:10404
	ds_write_b32 v70, v44 offset:10408
	ds_write_b32 v70, v45 offset:10412
	s_waitcnt vmcnt(6)
	ds_write_b32 v70, v46 offset:11440
	ds_write_b32 v70, v47 offset:11444
	ds_write_b32 v70, v48 offset:11448
	ds_write_b32 v70, v49 offset:11452
	s_waitcnt vmcnt(5)
	ds_write_b32 v70, v50 offset:12480
	ds_write_b32 v70, v51 offset:12484
	ds_write_b32 v70, v52 offset:12488
	ds_write_b32 v70, v53 offset:12492
	s_waitcnt vmcnt(4)
	ds_write_b32 v70, v54 offset:13520
	ds_write_b32 v70, v55 offset:13524
	ds_write_b32 v70, v56 offset:13528
	ds_write_b32 v70, v57 offset:13532
	s_waitcnt vmcnt(3)
	ds_write_b32 v70, v58 offset:14560
	ds_write_b32 v70, v59 offset:14564
	ds_write_b32 v70, v60 offset:14568
	ds_write_b32 v70, v61 offset:14572
	s_waitcnt vmcnt(2)
; #define LAS __attribute__((address_space(3)))
; __device__ __forceinline__ unsigned cvtpk(float lo, float hi) { f32x2_t v = {lo, hi}; bf16x2_t b = __builtin_convertvector(v, bf16x2_t); return __builtin_bit_cast(unsigned, b); }
; __device__ __forceinline__ void tr_all(const float* const* in, unsigned char* ws, LAS float* scr, int gw, int ngw, int lane, const TrRanges rg) {
;     ...
;         f32x4 g0 = {1.f, 1.f, 1.f, 1.f}, g1 = {1.f, 1.f, 1.f, 1.f};
;         if (cur.gain) { g0 = *(const f32x4*)cur.gain; g1 = *(const f32x4*)(cur.gain + 4); }
;         asm volatile("s_waitcnt lgkmcnt(0)" ::: "memory");
;         const LAS float* rp = scr + (8 * (lane & 7)) * 65 + (lane >> 3);
; #pragma unroll
;         for (int j = 0; j < 8; ++j) { const LAS float* s = rp + 8 * j;
;             u32x4 o; o.x = cvtpk(s[0 * 65] * g0[0], s[1 * 65] * g0[1]); o.y = cvtpk(s[2 * 65] * g0[2], s[3 * 65] * g0[3]);
;             o.z = cvtpk(s[4 * 65] * g1[0], s[5 * 65] * g1[1]); o.w = cvtpk(s[6 * 65] * g1[2], s[7 * 65] * g1[3]);
;             if (cur.nts) __builtin_nontemporal_store(o, (u32x4*)(cur.dst + (size_t)(8 * j) * cur.K)); else *(u32x4*)(cur.dst + (size_t)(8 * j) * cur.K) = o; }
	ds_write_b32 v70, v62 offset:15600
	ds_write_b32 v70, v63 offset:15604
	ds_write_b32 v70, v64 offset:15608
	ds_write_b32 v70, v65 offset:15612
	s_add_u32 s100, s84, 0x8f00000
	s_addc_u32 s101, s85, 0
	s_waitcnt vmcnt(0) lgkmcnt(0)
	ds_read_b32 v2, v71
	ds_read_b32 v3, v71 offset:260
	ds_read_b32 v4, v71 offset:520
	ds_read_b32 v5, v71 offset:780
	ds_read_b32 v6, v71 offset:1040
	ds_read_b32 v7, v71 offset:1300
	ds_read_b32 v8, v71 offset:1560
	ds_read_b32 v9, v71 offset:1820
	ds_read_b32 v10, v71 offset:32
	ds_read_b32 v11, v71 offset:292
	ds_read_b32 v12, v71 offset:552
	ds_read_b32 v13, v71 offset:812
	ds_read_b32 v14, v71 offset:1072
	ds_read_b32 v15, v71 offset:1332
	ds_read_b32 v16, v71 offset:1592
	ds_read_b32 v17, v71 offset:1852
	ds_read_b32 v18, v71 offset:64
	ds_read_b32 v19, v71 offset:324
	ds_read_b32 v20, v71 offset:584
	ds_read_b32 v21, v71 offset:844
	ds_read_b32 v22, v71 offset:1104
	ds_read_b32 v23, v71 offset:1364
	ds_read_b32 v24, v71 offset:1624
	ds_read_b32 v25, v71 offset:1884
	ds_read_b32 v26, v71 offset:96
	ds_read_b32 v27, v71 offset:356
	ds_read_b32 v28, v71 offset:616
	ds_read_b32 v29, v71 offset:876
	ds_read_b32 v30, v71 offset:1136
	ds_read_b32 v31, v71 offset:1396
	ds_read_b32 v32, v71 offset:1656
	ds_read_b32 v33, v71 offset:1916
	ds_read_b32 v34, v71 offset:128
	ds_read_b32 v35, v71 offset:388
	ds_read_b32 v36, v71 offset:648
	ds_read_b32 v37, v71 offset:908
	ds_read_b32 v38, v71 offset:1168
	ds_read_b32 v39, v71 offset:1428
	ds_read_b32 v40, v71 offset:1688
	ds_read_b32 v41, v71 offset:1948
	ds_read_b32 v42, v71 offset:160
	ds_read_b32 v43, v71 offset:420
	ds_read_b32 v44, v71 offset:680
	ds_read_b32 v45, v71 offset:940
	ds_read_b32 v46, v71 offset:1200
	ds_read_b32 v47, v71 offset:1460
	ds_read_b32 v48, v71 offset:1720
	ds_read_b32 v49, v71 offset:1980
	ds_read_b32 v50, v71 offset:192
	ds_read_b32 v51, v71 offset:452
	ds_read_b32 v52, v71 offset:712
	ds_read_b32 v53, v71 offset:972
	ds_read_b32 v54, v71 offset:1232
	ds_read_b32 v55, v71 offset:1492
	ds_read_b32 v56, v71 offset:1752
	ds_read_b32 v57, v71 offset:2012
	ds_read_b32 v58, v71 offset:224
	ds_read_b32 v59, v71 offset:484
	ds_read_b32 v60, v71 offset:744
	ds_read_b32 v61, v71 offset:1004
	ds_read_b32 v62, v71 offset:1264
	ds_read_b32 v63, v71 offset:1524
	ds_read_b32 v64, v71 offset:1784
	ds_read_b32 v65, v71 offset:2044
	s_waitcnt lgkmcnt(15)
	v_mul_f32_e32 v2, v2, v74
	v_mul_f32_e32 v3, v3, v75
	v_mul_f32_e32 v4, v4, v76
	v_mul_f32_e32 v5, v5, v77
	v_mul_f32_e32 v6, v6, v78
	v_mul_f32_e32 v7, v7, v79
	v_mul_f32_e32 v8, v8, v80
	v_mul_f32_e32 v9, v9, v81
	v_cvt_pk_bf16_f32 v192, v2, v3
	v_cvt_pk_bf16_f32 v193, v4, v5
	v_cvt_pk_bf16_f32 v194, v6, v7
	v_cvt_pk_bf16_f32 v195, v8, v9
	global_store_dwordx4 v72, v[192:195], s[100:101]
	s_waitcnt lgkmcnt(15)
	v_mul_f32_e32 v10, v10, v74
	v_mul_f32_e32 v11, v11, v75
	v_mul_f32_e32 v12, v12, v76
	v_mul_f32_e32 v13, v13, v77
	v_mul_f32_e32 v14, v14, v78
	v_mul_f32_e32 v15, v15, v79
	v_mul_f32_e32 v16, v16, v80
	v_mul_f32_e32 v17, v17, v81
	v_cvt_pk_bf16_f32 v196, v10, v11
	v_cvt_pk_bf16_f32 v197, v12, v13
	v_cvt_pk_bf16_f32 v198, v14, v15
	v_cvt_pk_bf16_f32 v199, v16, v17
	v_add_u32_e32 v68, 0x8000, v72
	global_store_dwordx4 v68, v[196:199], s[100:101]
	s_waitcnt lgkmcnt(15)
	v_mul_f32_e32 v18, v18, v74
	v_mul_f32_e32 v19, v19, v75
	v_mul_f32_e32 v20, v20, v76
	v_mul_f32_e32 v21, v21, v77
	v_mul_f32_e32 v22, v22, v78
	v_mul_f32_e32 v23, v23, v79
	v_mul_f32_e32 v24, v24, v80
	v_mul_f32_e32 v25, v25, v81
	v_cvt_pk_bf16_f32 v200, v18, v19
	v_cvt_pk_bf16_f32 v201, v20, v21
	v_cvt_pk_bf16_f32 v202, v22, v23
	v_cvt_pk_bf16_f32 v203, v24, v25
	v_add_u32_e32 v67, 0x10000, v72
	global_store_dwordx4 v67, v[200:203], s[100:101]
	s_waitcnt lgkmcnt(15)
	v_mul_f32_e32 v26, v26, v74
	v_mul_f32_e32 v27, v27, v75
	v_mul_f32_e32 v28, v28, v76
	v_mul_f32_e32 v29, v29, v77
	v_mul_f32_e32 v30, v30, v78
	v_mul_f32_e32 v31, v31, v79
	v_mul_f32_e32 v32, v32, v80
	v_mul_f32_e32 v33, v33, v81
	v_cvt_pk_bf16_f32 v204, v26, v27
	v_cvt_pk_bf16_f32 v205, v28, v29
	v_cvt_pk_bf16_f32 v206, v30, v31
	v_cvt_pk_bf16_f32 v207, v32, v33
	v_add_u32_e32 v68, 0x18000, v72
	global_store_dwordx4 v68, v[204:207], s[100:101]
	s_waitcnt lgkmcnt(15)
	v_mul_f32_e32 v34, v34, v74
	v_mul_f32_e32 v35, v35, v75
	v_mul_f32_e32 v36, v36, v76
	v_mul_f32_e32 v37, v37, v77
	v_mul_f32_e32 v38, v38, v78
	v_mul_f32_e32 v39, v39, v79
	v_mul_f32_e32 v40, v40, v80
	v_mul_f32_e32 v41, v41, v81
	v_cvt_pk_bf16_f32 v208, v34, v35
	v_cvt_pk_bf16_f32 v209, v36, v37
	v_cvt_pk_bf16_f32 v210, v38, v39
	v_cvt_pk_bf16_f32 v211, v40, v41
	v_add_u32_e32 v67, 0x20000, v72
	global_store_dwordx4 v67, v[208:211], s[100:101]
	s_waitcnt lgkmcnt(15)
	v_mul_f32_e32 v42, v42, v74
	v_mul_f32_e32 v43, v43, v75
	v_mul_f32_e32 v44, v44, v76
	v_mul_f32_e32 v45, v45, v77
	v_mul_f32_e32 v46, v46, v78
	v_mul_f32_e32 v47, v47, v79
	v_mul_f32_e32 v48, v48, v80
	v_mul_f32_e32 v49, v49, v81
	v_cvt_pk_bf16_f32 v212, v42, v43
	v_cvt_pk_bf16_f32 v213, v44, v45
	v_cvt_pk_bf16_f32 v214, v46, v47
	v_cvt_pk_bf16_f32 v215, v48, v49
	v_add_u32_e32 v68, 0x28000, v72
	global_store_dwordx4 v68, v[212:215], s[100:101]
	s_waitcnt lgkmcnt(8)
	v_mul_f32_e32 v50, v50, v74
	v_mul_f32_e32 v51, v51, v75
	v_mul_f32_e32 v52, v52, v76
	v_mul_f32_e32 v53, v53, v77
	v_mul_f32_e32 v54, v54, v78
	v_mul_f32_e32 v55, v55, v79
	v_mul_f32_e32 v56, v56, v80
	v_mul_f32_e32 v57, v57, v81
	v_cvt_pk_bf16_f32 v216, v50, v51
	v_cvt_pk_bf16_f32 v217, v52, v53
	v_cvt_pk_bf16_f32 v218, v54, v55
	v_cvt_pk_bf16_f32 v219, v56, v57
	v_add_u32_e32 v67, 0x30000, v72
	global_store_dwordx4 v67, v[216:219], s[100:101]
	s_waitcnt lgkmcnt(0)
	v_mul_f32_e32 v58, v58, v74
	v_mul_f32_e32 v59, v59, v75
	v_mul_f32_e32 v60, v60, v76
	v_mul_f32_e32 v61, v61, v77
	v_mul_f32_e32 v62, v62, v78
	v_mul_f32_e32 v63, v63, v79
	v_mul_f32_e32 v64, v64, v80
	v_mul_f32_e32 v65, v65, v81
	v_cvt_pk_bf16_f32 v220, v58, v59
	v_cvt_pk_bf16_f32 v221, v60, v61
	v_cvt_pk_bf16_f32 v222, v62, v63
	v_cvt_pk_bf16_f32 v223, v64, v65
	v_add_u32_e32 v68, 0x38000, v72
	global_store_dwordx4 v68, v[220:223], s[100:101]
	s_branch .LBB0_339
; __device__ __forceinline__ TrItem tr_decode(int it, const float* const* in, unsigned char* ws, int lane) {
;     ...
;     else if ((r -= 2048) < 1024) { W = in[15]; WT = (bf16_t*)(ws + WS_WO); nts = true; woh = true; }
;     else if ((r -= 1024) < 5632) { kind = 1; W = in[17]; W2 = in[18]; N = FF; ndb = 176; gain = in[16]; WT = (bf16_t*)(ws + WS_W2GU); nts = true; }
;     else { r -= 5632; W = in[19]; K = FF; WT = (bf16_t*)(ws + WS_W2D); }
;     ...
;     constexpr int KL = TR_ORDER, DL = 3 - TR_ORDER;
;     const int rh = r >> 3, rl = r & 7, nq = ndb >> DL, kbh = rh / nq, dbh = rh - kbh * nq;
;     const int kb = (kbh << KL) + (rl >> DL), db = (dbh << DL) + (rl & ((1 << DL) - 1)), d0 = db * 64, k0 = kb * 64;
;     ...
;     const int kb = r / ndb, db = r - kb * ndb, d0 = db * 64, k0 = kb * 64;
;     ...
;     const int blk = d0 + 32 * ((lane & 15) >> 3);
;     const float* src = W; int s0 = blk;
;     if (kind == 1) { const int pn = blk >> 8, bj = (blk >> 7) & 1, o = blk & 127; src = bj ? W2 : W; s0 = pn * 128 + o; }
;     else if (kind == 2) s0 = win_src(blk);
;     TrItem t; t.src = src + (size_t)(k0 + (lane >> 4)) * N + s0 + 4 * (lane & 7); t.gain = gain ? gain + k0 + 8 * (lane & 7) : nullptr;
;     t.dst = WT + (size_t)(d0 + (lane >> 3)) * K + k0 + 8 * (lane & 7); t.N = N; t.K = K; t.nts = nts && TR_NTS;
;     if (woh) { t.dst = WT + ((size_t)((k0 >> 9) * 2048 + d0 + (lane >> 3))) * 512 + (k0 & 511) + 8 * (lane & 7); t.K = 512; }
;     return t;
; }
;     __device__ __forceinline__ int count() const { return (e0 - b0) + (e1 - b1) + (e2 - b2); }
; __device__ __forceinline__ void tr_all(const float* const* in, unsigned char* ws, LAS float* scr, int gw, int ngw, int lane, const TrRanges rg) {
;     const int TR_CNT = rg.count();
;     if (gw >= TR_CNT) return;
;     TrItem cur = tr_decode(rg.item(gw), in, ws, lane);
;     f32x4 v[16];
; #pragma unroll
;     for (int i = 0; i < 16; ++i) v[i] = TR_LOAD((const f32x4*)(cur.src + (size_t)(4 * i) * cur.N));
;     for (int it = gw; it < TR_CNT; it += ngw) {
;         const int nit = it + ngw; const bool hn = nit < TR_CNT;
;         TrItem nx = cur; f32x4 w[16];
;         if (hn) { nx = tr_decode(rg.item(nit), in, ws, lane);
; #pragma unroll
;             for (int i = 0; i < 16; ++i) w[i] = TR_LOAD((const f32x4*)(nx.src + (size_t)(4 * i) * nx.N)); }
;         LAS float* wp = scr + (lane >> 4) * 65 + 4 * (lane & 15);
; #pragma unroll
.Lseam_cv_0_1:
	s_cmp_gt_u32 s98, 7
	s_cbranch_scc1 .LBB0_339
	s_mov_b64 exec, -1
	s_lshl_b32 s99, s87, 1
	s_add_i32 s99, s99, s98
	s_add_i32 s99, s99, 0xfffffffa
	s_lshr_b32 s100, s99, 3
	s_lshr_b32 s101, s100, 3
	s_and_b32 s100, s100, 7
	s_and_b32 vcc_lo, s99, 7
	s_lshr_b32 vcc_hi, vcc_lo, 2
	s_lshl_b32 s101, s101, 1
	s_add_i32 s101, s101, vcc_hi
	s_and_b32 vcc_lo, vcc_lo, 3
	s_lshl_b32 s100, s100, 2
	s_add_i32 s100, s100, vcc_lo
	s_lshl_b32 s101, s101, 6
	s_lshl_b32 s100, s100, 6
	v_and_b32_e32 v66, 63, v1
	v_lshrrev_b32_e32 v67, 4, v66
	v_and_b32_e32 v68, 15, v66
	v_and_b32_e32 v73, 7, v66
	v_lshrrev_b32_e32 v72, 3, v66
	s_mul_i32 s99, s98, 0x4100
	v_mul_u32_u24_e32 v70, 0x104, v67
	v_lshl_add_u32 v70, v68, 4, v70
	v_add_u32_e32 v70, s99, v70
	v_mul_u32_u24_e32 v71, 0x820, v73
	v_lshl_add_u32 v71, v72, 2, v71
	v_add_u32_e32 v71, s99, v71
	s_lshl_b32 s99, s101, 13
	s_lshl_b32 vcc_lo, s100, 2
	s_add_i32 s99, s99, vcc_lo
	v_lshlrev_b32_e32 v69, 13, v67
	v_lshl_add_u32 v69, v68, 4, v69
	v_add_u32_e32 v69, s99, v69
	s_lshr_b32 s99, s101, 9
	s_lshl_b32 s99, s99, 21
	s_lshl_b32 vcc_lo, s100, 10
	s_add_i32 s99, s99, vcc_lo
	s_and_b32 vcc_lo, s101, 0x1ff
	s_lshl_b32 vcc_lo, vcc_lo, 1
	s_add_i32 s99, s99, vcc_lo
	v_lshlrev_b32_e32 v72, 10, v72
	v_lshl_add_u32 v72, v73, 4, v72
	v_add_u32_e32 v72, s99, v72
	v_readlane_b32 s100, v254, 32
	v_readlane_b32 s101, v254, 33
	s_nop 4
	global_load_dwordx4 v[2:5], v69, s[100:101] nt
	v_add_u32_e32 v68, 0x8000, v69
	global_load_dwordx4 v[6:9], v68, s[100:101] nt
	v_add_u32_e32 v67, 0x10000, v69
	global_load_dwordx4 v[10:13], v67, s[100:101] nt
	v_add_u32_e32 v68, 0x18000, v69
	global_load_dwordx4 v[14:17], v68, s[100:101] nt
	v_add_u32_e32 v67, 0x20000, v69
	global_load_dwordx4 v[18:21], v67, s[100:101] nt
	v_add_u32_e32 v68, 0x28000, v69
	global_load_dwordx4 v[22:25], v68, s[100:101] nt
	v_add_u32_e32 v67, 0x30000, v69
	global_load_dwordx4 v[26:29], v67, s[100:101] nt
	v_add_u32_e32 v68, 0x38000, v69
	global_load_dwordx4 v[30:33], v68, s[100:101] nt
	v_add_u32_e32 v67, 0x40000, v69
	global_load_dwordx4 v[34:37], v67, s[100:101] nt
	v_add_u32_e32 v68, 0x48000, v69
	global_load_dwordx4 v[38:41], v68, s[100:101] nt
	v_add_u32_e32 v67, 0x50000, v69
	global_load_dwordx4 v[42:45], v67, s[100:101] nt
	v_add_u32_e32 v68, 0x58000, v69
	global_load_dwordx4 v[46:49], v68, s[100:101] nt
	v_add_u32_e32 v67, 0x60000, v69
	global_load_dwordx4 v[50:53], v67, s[100:101] nt
	v_add_u32_e32 v68, 0x68000, v69
	global_load_dwordx4 v[54:57], v68, s[100:101] nt
	v_add_u32_e32 v67, 0x70000, v69
	global_load_dwordx4 v[58:61], v67, s[100:101] nt
	v_add_u32_e32 v68, 0x78000, v69
	global_load_dwordx4 v[62:65], v68, s[100:101] nt
	s_waitcnt vmcnt(15)
	ds_write_b32 v70, v2
	ds_write_b32 v70, v3 offset:4
	ds_write_b32 v70, v4 offset:8
	ds_write_b32 v70, v5 offset:12
	s_waitcnt vmcnt(14)
	ds_write_b32 v70, v6 offset:1040
	ds_write_b32 v70, v7 offset:1044
	ds_write_b32 v70, v8 offset:1048
	ds_write_b32 v70, v9 offset:1052
	s_waitcnt vmcnt(13)
	ds_write_b32 v70, v10 offset:2080
	ds_write_b32 v70, v11 offset:2084
	ds_write_b32 v70, v12 offset:2088
	ds_write_b32 v70, v13 offset:2092
	s_waitcnt vmcnt(12)
	ds_write_b32 v70, v14 offset:3120
	ds_write_b32 v70, v15 offset:3124
	ds_write_b32 v70, v16 offset:3128
	ds_write_b32 v70, v17 offset:3132
	s_waitcnt vmcnt(11)
	ds_write_b32 v70, v18 offset:4160
	ds_write_b32 v70, v19 offset:4164
	ds_write_b32 v70, v20 offset:4168
	ds_write_b32 v70, v21 offset:4172
	s_waitcnt vmcnt(10)
	ds_write_b32 v70, v22 offset:5200
	ds_write_b32 v70, v23 offset:5204
	ds_write_b32 v70, v24 offset:5208
	ds_write_b32 v70, v25 offset:5212
	s_waitcnt vmcnt(9)
	ds_write_b32 v70, v26 offset:6240
	ds_write_b32 v70, v27 offset:6244
	ds_write_b32 v70, v28 offset:6248
	ds_write_b32 v70, v29 offset:6252
	s_waitcnt vmcnt(8)
	ds_write_b32 v70, v30 offset:7280
	ds_write_b32 v70, v31 offset:7284
	ds_write_b32 v70, v32 offset:7288
	ds_write_b32 v70, v33 offset:7292
	s_waitcnt vmcnt(7)
	ds_write_b32 v70, v34 offset:8320
	ds_write_b32 v70, v35 offset:8324
	ds_write_b32 v70, v36 offset:8328
	ds_write_b32 v70, v37 offset:8332
	s_waitcnt vmcnt(6)
	ds_write_b32 v70, v38 offset:9360
	ds_write_b32 v70, v39 offset:9364
	ds_write_b32 v70, v40 offset:9368
	ds_write_b32 v70, v41 offset:9372
	s_waitcnt vmcnt(5)
	ds_write_b32 v70, v42 offset:10400
	ds_write_b32 v70, v43 offset:10404
	ds_write_b32 v70, v44 offset:10408
	ds_write_b32 v70, v45 offset:10412
	s_waitcnt vmcnt(4)
	ds_write_b32 v70, v46 offset:11440
	ds_write_b32 v70, v47 offset:11444
	ds_write_b32 v70, v48 offset:11448
	ds_write_b32 v70, v49 offset:11452
	s_waitcnt vmcnt(3)
; #define LAS __attribute__((address_space(3)))
; __device__ __forceinline__ unsigned cvtpk(float lo, float hi) { f32x2_t v = {lo, hi}; bf16x2_t b = __builtin_convertvector(v, bf16x2_t); return __builtin_bit_cast(unsigned, b); }
; __device__ __forceinline__ void tr_all(const float* const* in, unsigned char* ws, LAS float* scr, int gw, int ngw, int lane, const TrRanges rg) {
;     ...
;         asm volatile("s_waitcnt lgkmcnt(0)" ::: "memory");
;         const LAS float* rp = scr + (8 * (lane & 7)) * 65 + (lane >> 3);
; #pragma unroll
;         for (int j = 0; j < 8; ++j) { const LAS float* s = rp + 8 * j;
;             u32x4 o; o.x = cvtpk(s[0 * 65] * g0[0], s[1 * 65] * g0[1]); o.y = cvtpk(s[2 * 65] * g0[2], s[3 * 65] * g0[3]);
;             o.z = cvtpk(s[4 * 65] * g1[0], s[5 * 65] * g1[1]); o.w = cvtpk(s[6 * 65] * g1[2], s[7 * 65] * g1[3]);
;             if (cur.nts) __builtin_nontemporal_store(o, (u32x4*)(cur.dst + (size_t)(8 * j) * cur.K)); else *(u32x4*)(cur.dst + (size_t)(8 * j) * cur.K) = o; }
	ds_write_b32 v70, v50 offset:12480
	ds_write_b32 v70, v51 offset:12484
	ds_write_b32 v70, v52 offset:12488
	ds_write_b32 v70, v53 offset:12492
	s_waitcnt vmcnt(2)
	ds_write_b32 v70, v54 offset:13520
	ds_write_b32 v70, v55 offset:13524
	ds_write_b32 v70, v56 offset:13528
	ds_write_b32 v70, v57 offset:13532
	s_waitcnt vmcnt(1)
	ds_write_b32 v70, v58 offset:14560
	ds_write_b32 v70, v59 offset:14564
	ds_write_b32 v70, v60 offset:14568
	ds_write_b32 v70, v61 offset:14572
	s_waitcnt vmcnt(0)
	ds_write_b32 v70, v62 offset:15600
	ds_write_b32 v70, v63 offset:15604
	ds_write_b32 v70, v64 offset:15608
	ds_write_b32 v70, v65 offset:15612
	s_add_u32 s100, s84, 0x8700000
	s_addc_u32 s101, s85, 0
	s_waitcnt lgkmcnt(0)
	ds_read_b32 v2, v71
	ds_read_b32 v3, v71 offset:260
	ds_read_b32 v4, v71 offset:520
	ds_read_b32 v5, v71 offset:780
	ds_read_b32 v6, v71 offset:1040
	ds_read_b32 v7, v71 offset:1300
	ds_read_b32 v8, v71 offset:1560
	ds_read_b32 v9, v71 offset:1820
	ds_read_b32 v10, v71 offset:32
	ds_read_b32 v11, v71 offset:292
	ds_read_b32 v12, v71 offset:552
	ds_read_b32 v13, v71 offset:812
	ds_read_b32 v14, v71 offset:1072
	ds_read_b32 v15, v71 offset:1332
	ds_read_b32 v16, v71 offset:1592
	ds_read_b32 v17, v71 offset:1852
	ds_read_b32 v18, v71 offset:64
	ds_read_b32 v19, v71 offset:324
	ds_read_b32 v20, v71 offset:584
	ds_read_b32 v21, v71 offset:844
	ds_read_b32 v22, v71 offset:1104
	ds_read_b32 v23, v71 offset:1364
	ds_read_b32 v24, v71 offset:1624
	ds_read_b32 v25, v71 offset:1884
	ds_read_b32 v26, v71 offset:96
	ds_read_b32 v27, v71 offset:356
	ds_read_b32 v28, v71 offset:616
	ds_read_b32 v29, v71 offset:876
	ds_read_b32 v30, v71 offset:1136
	ds_read_b32 v31, v71 offset:1396
	ds_read_b32 v32, v71 offset:1656
	ds_read_b32 v33, v71 offset:1916
	ds_read_b32 v34, v71 offset:128
	ds_read_b32 v35, v71 offset:388
	ds_read_b32 v36, v71 offset:648
	ds_read_b32 v37, v71 offset:908
	ds_read_b32 v38, v71 offset:1168
	ds_read_b32 v39, v71 offset:1428
	ds_read_b32 v40, v71 offset:1688
	ds_read_b32 v41, v71 offset:1948
	ds_read_b32 v42, v71 offset:160
	ds_read_b32 v43, v71 offset:420
	ds_read_b32 v44, v71 offset:680
	ds_read_b32 v45, v71 offset:940
	ds_read_b32 v46, v71 offset:1200
	ds_read_b32 v47, v71 offset:1460
	ds_read_b32 v48, v71 offset:1720
	ds_read_b32 v49, v71 offset:1980
	ds_read_b32 v50, v71 offset:192
	ds_read_b32 v51, v71 offset:452
	ds_read_b32 v52, v71 offset:712
	ds_read_b32 v53, v71 offset:972
	ds_read_b32 v54, v71 offset:1232
	ds_read_b32 v55, v71 offset:1492
	ds_read_b32 v56, v71 offset:1752
	ds_read_b32 v57, v71 offset:2012
	ds_read_b32 v58, v71 offset:224
	ds_read_b32 v59, v71 offset:484
	ds_read_b32 v60, v71 offset:744
	ds_read_b32 v61, v71 offset:1004
	ds_read_b32 v62, v71 offset:1264
	ds_read_b32 v63, v71 offset:1524
	ds_read_b32 v64, v71 offset:1784
	ds_read_b32 v65, v71 offset:2044
	s_waitcnt lgkmcnt(15)
	v_cvt_pk_bf16_f32 v192, v2, v3
	v_cvt_pk_bf16_f32 v193, v4, v5
	v_cvt_pk_bf16_f32 v194, v6, v7
	v_cvt_pk_bf16_f32 v195, v8, v9
	global_store_dwordx4 v72, v[192:195], s[100:101]
	s_waitcnt lgkmcnt(15)
	v_cvt_pk_bf16_f32 v196, v10, v11
	v_cvt_pk_bf16_f32 v197, v12, v13
	v_cvt_pk_bf16_f32 v198, v14, v15
	v_cvt_pk_bf16_f32 v199, v16, v17
	v_add_u32_e32 v68, 0x2000, v72
	global_store_dwordx4 v68, v[196:199], s[100:101]
	s_waitcnt lgkmcnt(15)
	v_cvt_pk_bf16_f32 v200, v18, v19
	v_cvt_pk_bf16_f32 v201, v20, v21
	v_cvt_pk_bf16_f32 v202, v22, v23
	v_cvt_pk_bf16_f32 v203, v24, v25
	v_add_u32_e32 v67, 0x4000, v72
	global_store_dwordx4 v67, v[200:203], s[100:101]
	s_waitcnt lgkmcnt(15)
	v_cvt_pk_bf16_f32 v204, v26, v27
	v_cvt_pk_bf16_f32 v205, v28, v29
	v_cvt_pk_bf16_f32 v206, v30, v31
	v_cvt_pk_bf16_f32 v207, v32, v33
	v_add_u32_e32 v68, 0x6000, v72
	global_store_dwordx4 v68, v[204:207], s[100:101]
	s_waitcnt lgkmcnt(15)
	v_cvt_pk_bf16_f32 v208, v34, v35
	v_cvt_pk_bf16_f32 v209, v36, v37
	v_cvt_pk_bf16_f32 v210, v38, v39
	v_cvt_pk_bf16_f32 v211, v40, v41
	v_add_u32_e32 v67, 0x8000, v72
	global_store_dwordx4 v67, v[208:211], s[100:101]
	s_waitcnt lgkmcnt(15)
	v_cvt_pk_bf16_f32 v212, v42, v43
	v_cvt_pk_bf16_f32 v213, v44, v45
	v_cvt_pk_bf16_f32 v214, v46, v47
	v_cvt_pk_bf16_f32 v215, v48, v49
	v_add_u32_e32 v68, 0xa000, v72
	global_store_dwordx4 v68, v[212:215], s[100:101]
	s_waitcnt lgkmcnt(8)
	v_cvt_pk_bf16_f32 v216, v50, v51
	v_cvt_pk_bf16_f32 v217, v52, v53
	v_cvt_pk_bf16_f32 v218, v54, v55
	v_cvt_pk_bf16_f32 v219, v56, v57
	v_add_u32_e32 v67, 0xc000, v72
	global_store_dwordx4 v67, v[216:219], s[100:101]
	s_waitcnt lgkmcnt(0)
	v_cvt_pk_bf16_f32 v220, v58, v59
	v_cvt_pk_bf16_f32 v221, v60, v61
	v_cvt_pk_bf16_f32 v222, v62, v63
	v_cvt_pk_bf16_f32 v223, v64, v65
	v_add_u32_e32 v68, 0xe000, v72
	global_store_dwordx4 v68, v[220:223], s[100:101]

; #define LAS __attribute__((address_space(3)))
; #define TR_LOAD(p) __builtin_nontemporal_load(p)
; __device__ __forceinline__ TrItem tr_decode(int it, const float* const* in, unsigned char* ws, int lane) {
;     ...
;     else if ((r -= 1024) < 5632) { kind = 1; W = in[17]; W2 = in[18]; N = FF; ndb = 176; gain = in[16]; WT = (bf16_t*)(ws + WS_W2GU); nts = true; }
;     else { r -= 5632; W = in[19]; K = FF; WT = (bf16_t*)(ws + WS_W2D); }
;     ...
;     constexpr int KL = TR_ORDER, DL = 3 - TR_ORDER;
;     const int rh = r >> 3, rl = r & 7, nq = ndb >> DL, kbh = rh / nq, dbh = rh - kbh * nq;
;     const int kb = (kbh << KL) + (rl >> DL), db = (dbh << DL) + (rl & ((1 << DL) - 1)), d0 = db * 64, k0 = kb * 64;
;     ...
;     const int kb = r / ndb, db = r - kb * ndb, d0 = db * 64, k0 = kb * 64;
;     ...
;     const int blk = d0 + 32 * ((lane & 15) >> 3);
;     const float* src = W; int s0 = blk;
;     if (kind == 1) { const int pn = blk >> 8, bj = (blk >> 7) & 1, o = blk & 127; src = bj ? W2 : W; s0 = pn * 128 + o; }
;     else if (kind == 2) s0 = win_src(blk);
;     TrItem t; t.src = src + (size_t)(k0 + (lane >> 4)) * N + s0 + 4 * (lane & 7); t.gain = gain ? gain + k0 + 8 * (lane & 7) : nullptr;
;     t.dst = WT + (size_t)(d0 + (lane >> 3)) * K + k0 + 8 * (lane & 7); t.N = N; t.K = K; t.nts = nts && TR_NTS;
;     if (woh) { t.dst = WT + ((size_t)((k0 >> 9) * 2048 + d0 + (lane >> 3))) * 512 + (k0 & 511) + 8 * (lane & 7); t.K = 512; }
;     return t;
; }
;     __device__ __forceinline__ int count() const { return (e0 - b0) + (e1 - b1) + (e2 - b2); }
; __device__ __forceinline__ void tr_all(const float* const* in, unsigned char* ws, LAS float* scr, int gw, int ngw, int lane, const TrRanges rg) {
;     const int TR_CNT = rg.count();
;     if (gw >= TR_CNT) return;
;     TrItem cur = tr_decode(rg.item(gw), in, ws, lane);
;     f32x4 v[16];
; #pragma unroll
;     for (int i = 0; i < 16; ++i) v[i] = TR_LOAD((const f32x4*)(cur.src + (size_t)(4 * i) * cur.N));
;     for (int it = gw; it < TR_CNT; it += ngw) {
;         const int nit = it + ngw; const bool hn = nit < TR_CNT;
;         TrItem nx = cur; f32x4 w[16];
;         if (hn) { nx = tr_decode(rg.item(nit), in, ws, lane);
; #pragma unroll
;             for (int i = 0; i < 16; ++i) w[i] = TR_LOAD((const f32x4*)(nx.src + (size_t)(4 * i) * nx.N)); }
;         LAS float* wp = scr + (lane >> 4) * 65 + 4 * (lane & 15);
; #pragma unroll
.Lseam_cv_1:
	s_cmp_lt_u32 s98, 2
	s_cbranch_scc1 .LBB0_570
	s_cmp_gt_u32 s98, 5
	s_cbranch_scc1 .Lseam_cv_1_1
	s_mov_b64 exec, -1
	s_lshl_b32 s99, s87, 2
	s_add_i32 s99, s99, s98
	s_add_i32 s99, s99, 0x9fe
	s_lshr_b32 s100, s99, 3
	s_mul_i32 s101, s100, 0x5d2
	s_lshr_b32 s101, s101, 16
	s_mul_i32 vcc_lo, s101, 44
	s_sub_i32 s100, s100, vcc_lo
	s_and_b32 vcc_lo, s99, 7
	s_lshr_b32 vcc_hi, vcc_lo, 2
	s_lshl_b32 s101, s101, 1
	s_add_i32 s101, s101, vcc_hi
	s_and_b32 vcc_lo, vcc_lo, 3
	s_lshl_b32 s100, s100, 2
	s_add_i32 s100, s100, vcc_lo
	s_lshl_b32 s101, s101, 6
	s_lshl_b32 s100, s100, 6
	v_and_b32_e32 v66, 63, v1
	v_lshrrev_b32_e32 v67, 4, v66
	v_and_b32_e32 v68, 15, v66
	v_and_b32_e32 v73, 7, v66
	v_lshrrev_b32_e32 v72, 3, v66
	s_mul_i32 s99, s98, 0x4100
	v_mul_u32_u24_e32 v70, 0x104, v67
	v_lshl_add_u32 v70, v68, 4, v70
	v_add_u32_e32 v70, s99, v70
	v_mul_u32_u24_e32 v71, 0x820, v73
	v_lshl_add_u32 v71, v72, 2, v71
	v_add_u32_e32 v71, s99, v71
	s_mul_i32 s99, s101, 0x1600
	s_lshr_b32 vcc_lo, s100, 8
	s_lshl_b32 vcc_lo, vcc_lo, 7
	s_add_i32 s99, s99, vcc_lo
	s_and_b32 vcc_lo, s100, 0x7f
	s_add_i32 s99, s99, vcc_lo
	s_lshl_b32 s99, s99, 2
	v_mul_u32_u24_e32 v69, 0x5800, v67
	v_lshl_add_u32 v69, v68, 4, v69
	v_add_u32_e32 v69, s99, v69
	s_lshl_b32 s99, s100, 12
	s_lshl_b32 vcc_lo, s101, 1
	s_add_i32 s99, s99, vcc_lo
	v_lshlrev_b32_e32 v72, 12, v72
	v_lshl_add_u32 v72, v73, 4, v72
	v_add_u32_e32 v72, s99, v72
	s_lshl_b32 s99, s101, 2
	v_lshlrev_b32_e32 v73, 5, v73
	v_add_u32_e32 v73, s99, v73
	s_nop 0
	s_bitcmp1_b32 s100, 7
	v_readlane_b32 s100, v254, 6
	v_readlane_b32 s101, v254, 7
	v_readlane_b32 s98, v254, 8
	v_readlane_b32 s99, v254, 9
	s_nop 3
	s_cselect_b32 s100, s98, s100
	s_cselect_b32 s101, s99, s101
	v_readlane_b32 s98, v254, 4
	v_readlane_b32 s99, v254, 5
	global_load_dwordx4 v[2:5], v69, s[100:101] nt
	v_add_u32_e32 v68, 0x16000, v69
	global_load_dwordx4 v[6:9], v68, s[100:101] nt
	v_add_u32_e32 v67, 0x2c000, v69
	global_load_dwordx4 v[10:13], v67, s[100:101] nt
	v_add_u32_e32 v68, 0x42000, v69
	global_load_dwordx4 v[14:17], v68, s[100:101] nt
	v_add_u32_e32 v67, 0x58000, v69
	global_load_dwordx4 v[18:21], v67, s[100:101] nt
	v_add_u32_e32 v68, 0x6e000, v69
	global_load_dwordx4 v[22:25], v68, s[100:101] nt
	v_add_u32_e32 v67, 0x84000, v69
	global_load_dwordx4 v[26:29], v67, s[100:101] nt
	v_add_u32_e32 v68, 0x9a000, v69
	global_load_dwordx4 v[30:33], v68, s[100:101] nt
	v_add_u32_e32 v67, 0xb0000, v69
	global_load_dwordx4 v[34:37], v67, s[100:101] nt
	v_add_u32_e32 v68, 0xc6000, v69
	global_load_dwordx4 v[38:41], v68, s[100:101] nt
	v_add_u32_e32 v67, 0xdc000, v69
	global_load_dwordx4 v[42:45], v67, s[100:101] nt
	v_add_u32_e32 v68, 0xf2000, v69
	global_load_dwordx4 v[46:49], v68, s[100:101] nt
	v_add_u32_e32 v67, 0x108000, v69
	global_load_dwordx4 v[50:53], v67, s[100:101] nt
	v_add_u32_e32 v68, 0x11e000, v69
	global_load_dwordx4 v[54:57], v68, s[100:101] nt
	v_add_u32_e32 v67, 0x134000, v69
	global_load_dwordx4 v[58:61], v67, s[100:101] nt
	v_add_u32_e32 v68, 0x14a000, v69
	global_load_dwordx4 v[62:65], v68, s[100:101] nt
	global_load_dwordx4 v[74:77], v73, s[98:99]
	global_load_dwordx4 v[78:81], v73, s[98:99] offset:16
	s_waitcnt vmcnt(17)
	ds_write_b32 v70, v2
	ds_write_b32 v70, v3 offset:4
	ds_write_b32 v70, v4 offset:8
	ds_write_b32 v70, v5 offset:12
	s_waitcnt vmcnt(16)
	ds_write_b32 v70, v6 offset:1040
	ds_write_b32 v70, v7 offset:1044
	ds_write_b32 v70, v8 offset:1048
	ds_write_b32 v70, v9 offset:1052
	s_waitcnt vmcnt(15)
	ds_write_b32 v70, v10 offset:2080
	ds_write_b32 v70, v11 offset:2084
	ds_write_b32 v70, v12 offset:2088
	ds_write_b32 v70, v13 offset:2092
	s_waitcnt vmcnt(14)
	ds_write_b32 v70, v14 offset:3120
	ds_write_b32 v70, v15 offset:3124
	ds_write_b32 v70, v16 offset:3128
	ds_write_b32 v70, v17 offset:3132
	s_waitcnt vmcnt(13)
	ds_write_b32 v70, v18 offset:4160
	ds_write_b32 v70, v19 offset:4164
	ds_write_b32 v70, v20 offset:4168
	ds_write_b32 v70, v21 offset:4172
	s_waitcnt vmcnt(12)
	ds_write_b32 v70, v22 offset:5200
	ds_write_b32 v70, v23 offset:5204
	ds_write_b32 v70, v24 offset:5208
	ds_write_b32 v70, v25 offset:5212
	s_waitcnt vmcnt(11)
	ds_write_b32 v70, v26 offset:6240
	ds_write_b32 v70, v27 offset:6244
	ds_write_b32 v70, v28 offset:6248
	ds_write_b32 v70, v29 offset:6252
	s_waitcnt vmcnt(10)
	ds_write_b32 v70, v30 offset:7280
	ds_write_b32 v70, v31 offset:7284
	ds_write_b32 v70, v32 offset:7288
	ds_write_b32 v70, v33 offset:7292
	s_waitcnt vmcnt(9)
	ds_write_b32 v70, v34 offset:8320
	ds_write_b32 v70, v35 offset:8324
	ds_write_b32 v70, v36 offset:8328
	ds_write_b32 v70, v37 offset:8332
	s_waitcnt vmcnt(8)
	ds_write_b32 v70, v38 offset:9360
	ds_write_b32 v70, v39 offset:9364
	ds_write_b32 v70, v40 offset:9368
	ds_write_b32 v70, v41 offset:9372
	s_waitcnt vmcnt(7)
	ds_write_b32 v70, v42 offset:10400
	ds_write_b32 v70, v43 offset:10404
	ds_write_b32 v70, v44 offset:10408
	ds_write_b32 v70, v45 offset:10412
	s_waitcnt vmcnt(6)
	ds_write_b32 v70, v46 offset:11440
	ds_write_b32 v70, v47 offset:11444
	ds_write_b32 v70, v48 offset:11448
	ds_write_b32 v70, v49 offset:11452
	s_waitcnt vmcnt(5)
	ds_write_b32 v70, v50 offset:12480
	ds_write_b32 v70, v51 offset:12484
	ds_write_b32 v70, v52 offset:12488
	ds_write_b32 v70, v53 offset:12492
	s_waitcnt vmcnt(4)
	ds_write_b32 v70, v54 offset:13520
	ds_write_b32 v70, v55 offset:13524
	ds_write_b32 v70, v56 offset:13528
	ds_write_b32 v70, v57 offset:13532
	s_waitcnt vmcnt(3)
	ds_write_b32 v70, v58 offset:14560
	ds_write_b32 v70, v59 offset:14564
	ds_write_b32 v70, v60 offset:14568
	ds_write_b32 v70, v61 offset:14572
	s_waitcnt vmcnt(2)
; #define LAS __attribute__((address_space(3)))
; __device__ __forceinline__ unsigned cvtpk(float lo, float hi) { f32x2_t v = {lo, hi}; bf16x2_t b = __builtin_convertvector(v, bf16x2_t); return __builtin_bit_cast(unsigned, b); }
; __device__ __forceinline__ void tr_all(const float* const* in, unsigned char* ws, LAS float* scr, int gw, int ngw, int lane, const TrRanges rg) {
;     ...
;         f32x4 g0 = {1.f, 1.f, 1.f, 1.f}, g1 = {1.f, 1.f, 1.f, 1.f};
;         if (cur.gain) { g0 = *(const f32x4*)cur.gain; g1 = *(const f32x4*)(cur.gain + 4); }
;         asm volatile("s_waitcnt lgkmcnt(0)" ::: "memory");
;         const LAS float* rp = scr + (8 * (lane & 7)) * 65 + (lane >> 3);
; #pragma unroll
;         for (int j = 0; j < 8; ++j) { const LAS float* s = rp + 8 * j;
;             u32x4 o; o.x = cvtpk(s[0 * 65] * g0[0], s[1 * 65] * g0[1]); o.y = cvtpk(s[2 * 65] * g0[2], s[3 * 65] * g0[3]);
;             o.z = cvtpk(s[4 * 65] * g1[0], s[5 * 65] * g1[1]); o.w = cvtpk(s[6 * 65] * g1[2], s[7 * 65] * g1[3]);
;             if (cur.nts) __builtin_nontemporal_store(o, (u32x4*)(cur.dst + (size_t)(8 * j) * cur.K)); else *(u32x4*)(cur.dst + (size_t)(8 * j) * cur.K) = o; }
	ds_write_b32 v70, v62 offset:15600
	ds_write_b32 v70, v63 offset:15604
	ds_write_b32 v70, v64 offset:15608
	ds_write_b32 v70, v65 offset:15612
	s_add_u32 s100, s84, 0x8f00000
	s_addc_u32 s101, s85, 0
	s_waitcnt vmcnt(0) lgkmcnt(0)
	ds_read_b32 v2, v71
	ds_read_b32 v3, v71 offset:260
	ds_read_b32 v4, v71 offset:520
	ds_read_b32 v5, v71 offset:780
	ds_read_b32 v6, v71 offset:1040
	ds_read_b32 v7, v71 offset:1300
	ds_read_b32 v8, v71 offset:1560
	ds_read_b32 v9, v71 offset:1820
	ds_read_b32 v10, v71 offset:32
	ds_read_b32 v11, v71 offset:292
	ds_read_b32 v12, v71 offset:552
	ds_read_b32 v13, v71 offset:812
	ds_read_b32 v14, v71 offset:1072
	ds_read_b32 v15, v71 offset:1332
	ds_read_b32 v16, v71 offset:1592
	ds_read_b32 v17, v71 offset:1852
	ds_read_b32 v18, v71 offset:64
	ds_read_b32 v19, v71 offset:324
	ds_read_b32 v20, v71 offset:584
	ds_read_b32 v21, v71 offset:844
	ds_read_b32 v22, v71 offset:1104
	ds_read_b32 v23, v71 offset:1364
	ds_read_b32 v24, v71 offset:1624
	ds_read_b32 v25, v71 offset:1884
	ds_read_b32 v26, v71 offset:96
	ds_read_b32 v27, v71 offset:356
	ds_read_b32 v28, v71 offset:616
	ds_read_b32 v29, v71 offset:876
	ds_read_b32 v30, v71 offset:1136
	ds_read_b32 v31, v71 offset:1396
	ds_read_b32 v32, v71 offset:1656
	ds_read_b32 v33, v71 offset:1916
	ds_read_b32 v34, v71 offset:128
	ds_read_b32 v35, v71 offset:388
	ds_read_b32 v36, v71 offset:648
	ds_read_b32 v37, v71 offset:908
	ds_read_b32 v38, v71 offset:1168
	ds_read_b32 v39, v71 offset:1428
	ds_read_b32 v40, v71 offset:1688
	ds_read_b32 v41, v71 offset:1948
	ds_read_b32 v42, v71 offset:160
	ds_read_b32 v43, v71 offset:420
	ds_read_b32 v44, v71 offset:680
	ds_read_b32 v45, v71 offset:940
	ds_read_b32 v46, v71 offset:1200
	ds_read_b32 v47, v71 offset:1460
	ds_read_b32 v48, v71 offset:1720
	ds_read_b32 v49, v71 offset:1980
	ds_read_b32 v50, v71 offset:192
	ds_read_b32 v51, v71 offset:452
	ds_read_b32 v52, v71 offset:712
	ds_read_b32 v53, v71 offset:972
	ds_read_b32 v54, v71 offset:1232
	ds_read_b32 v55, v71 offset:1492
	ds_read_b32 v56, v71 offset:1752
	ds_read_b32 v57, v71 offset:2012
	ds_read_b32 v58, v71 offset:224
	ds_read_b32 v59, v71 offset:484
	ds_read_b32 v60, v71 offset:744
	ds_read_b32 v61, v71 offset:1004
	ds_read_b32 v62, v71 offset:1264
	ds_read_b32 v63, v71 offset:1524
	ds_read_b32 v64, v71 offset:1784
	ds_read_b32 v65, v71 offset:2044
	s_waitcnt lgkmcnt(15)
	v_mul_f32_e32 v2, v2, v74
	v_mul_f32_e32 v3, v3, v75
	v_mul_f32_e32 v4, v4, v76
	v_mul_f32_e32 v5, v5, v77
	v_mul_f32_e32 v6, v6, v78
	v_mul_f32_e32 v7, v7, v79
	v_mul_f32_e32 v8, v8, v80
	v_mul_f32_e32 v9, v9, v81
	v_cvt_pk_bf16_f32 v192, v2, v3
	v_cvt_pk_bf16_f32 v193, v4, v5
	v_cvt_pk_bf16_f32 v194, v6, v7
	v_cvt_pk_bf16_f32 v195, v8, v9
	global_store_dwordx4 v72, v[192:195], s[100:101]
	s_waitcnt lgkmcnt(15)
	v_mul_f32_e32 v10, v10, v74
	v_mul_f32_e32 v11, v11, v75
	v_mul_f32_e32 v12, v12, v76
	v_mul_f32_e32 v13, v13, v77
	v_mul_f32_e32 v14, v14, v78
	v_mul_f32_e32 v15, v15, v79
	v_mul_f32_e32 v16, v16, v80
	v_mul_f32_e32 v17, v17, v81
	v_cvt_pk_bf16_f32 v196, v10, v11
	v_cvt_pk_bf16_f32 v197, v12, v13
	v_cvt_pk_bf16_f32 v198, v14, v15
	v_cvt_pk_bf16_f32 v199, v16, v17
	v_add_u32_e32 v68, 0x8000, v72
	global_store_dwordx4 v68, v[196:199], s[100:101]
	s_waitcnt lgkmcnt(15)
	v_mul_f32_e32 v18, v18, v74
	v_mul_f32_e32 v19, v19, v75
	v_mul_f32_e32 v20, v20, v76
	v_mul_f32_e32 v21, v21, v77
	v_mul_f32_e32 v22, v22, v78
	v_mul_f32_e32 v23, v23, v79
	v_mul_f32_e32 v24, v24, v80
	v_mul_f32_e32 v25, v25, v81
	v_cvt_pk_bf16_f32 v200, v18, v19
	v_cvt_pk_bf16_f32 v201, v20, v21
	v_cvt_pk_bf16_f32 v202, v22, v23
	v_cvt_pk_bf16_f32 v203, v24, v25
	v_add_u32_e32 v67, 0x10000, v72
	global_store_dwordx4 v67, v[200:203], s[100:101]
	s_waitcnt lgkmcnt(15)
	v_mul_f32_e32 v26, v26, v74
	v_mul_f32_e32 v27, v27, v75
	v_mul_f32_e32 v28, v28, v76
	v_mul_f32_e32 v29, v29, v77
	v_mul_f32_e32 v30, v30, v78
	v_mul_f32_e32 v31, v31, v79
	v_mul_f32_e32 v32, v32, v80
	v_mul_f32_e32 v33, v33, v81
	v_cvt_pk_bf16_f32 v204, v26, v27
	v_cvt_pk_bf16_f32 v205, v28, v29
	v_cvt_pk_bf16_f32 v206, v30, v31
	v_cvt_pk_bf16_f32 v207, v32, v33
	v_add_u32_e32 v68, 0x18000, v72
	global_store_dwordx4 v68, v[204:207], s[100:101]
	s_waitcnt lgkmcnt(15)
	v_mul_f32_e32 v34, v34, v74
	v_mul_f32_e32 v35, v35, v75
	v_mul_f32_e32 v36, v36, v76
	v_mul_f32_e32 v37, v37, v77
	v_mul_f32_e32 v38, v38, v78
	v_mul_f32_e32 v39, v39, v79
	v_mul_f32_e32 v40, v40, v80
	v_mul_f32_e32 v41, v41, v81
	v_cvt_pk_bf16_f32 v208, v34, v35
	v_cvt_pk_bf16_f32 v209, v36, v37
	v_cvt_pk_bf16_f32 v210, v38, v39
	v_cvt_pk_bf16_f32 v211, v40, v41
	v_add_u32_e32 v67, 0x20000, v72
	global_store_dwordx4 v67, v[208:211], s[100:101]
	s_waitcnt lgkmcnt(15)
	v_mul_f32_e32 v42, v42, v74
	v_mul_f32_e32 v43, v43, v75
	v_mul_f32_e32 v44, v44, v76
	v_mul_f32_e32 v45, v45, v77
	v_mul_f32_e32 v46, v46, v78
	v_mul_f32_e32 v47, v47, v79
	v_mul_f32_e32 v48, v48, v80
	v_mul_f32_e32 v49, v49, v81
	v_cvt_pk_bf16_f32 v212, v42, v43
	v_cvt_pk_bf16_f32 v213, v44, v45
	v_cvt_pk_bf16_f32 v214, v46, v47
	v_cvt_pk_bf16_f32 v215, v48, v49
	v_add_u32_e32 v68, 0x28000, v72
	global_store_dwordx4 v68, v[212:215], s[100:101]
	s_waitcnt lgkmcnt(8)
	v_mul_f32_e32 v50, v50, v74
	v_mul_f32_e32 v51, v51, v75
	v_mul_f32_e32 v52, v52, v76
	v_mul_f32_e32 v53, v53, v77
	v_mul_f32_e32 v54, v54, v78
	v_mul_f32_e32 v55, v55, v79
	v_mul_f32_e32 v56, v56, v80
	v_mul_f32_e32 v57, v57, v81
	v_cvt_pk_bf16_f32 v216, v50, v51
	v_cvt_pk_bf16_f32 v217, v52, v53
	v_cvt_pk_bf16_f32 v218, v54, v55
	v_cvt_pk_bf16_f32 v219, v56, v57
	v_add_u32_e32 v67, 0x30000, v72
	global_store_dwordx4 v67, v[216:219], s[100:101]
	s_waitcnt lgkmcnt(0)
	v_mul_f32_e32 v58, v58, v74
	v_mul_f32_e32 v59, v59, v75
	v_mul_f32_e32 v60, v60, v76
	v_mul_f32_e32 v61, v61, v77
	v_mul_f32_e32 v62, v62, v78
	v_mul_f32_e32 v63, v63, v79
	v_mul_f32_e32 v64, v64, v80
	v_mul_f32_e32 v65, v65, v81
	v_cvt_pk_bf16_f32 v220, v58, v59
	v_cvt_pk_bf16_f32 v221, v60, v61
	v_cvt_pk_bf16_f32 v222, v62, v63
	v_cvt_pk_bf16_f32 v223, v64, v65
	v_add_u32_e32 v68, 0x38000, v72
	global_store_dwordx4 v68, v[220:223], s[100:101]
	s_branch .LBB0_570
; __device__ __forceinline__ TrItem tr_decode(int it, const float* const* in, unsigned char* ws, int lane) {
;     ...
;     else if ((r -= 2048) < 1024) { W = in[15]; WT = (bf16_t*)(ws + WS_WO); nts = true; woh = true; }
;     else if ((r -= 1024) < 5632) { kind = 1; W = in[17]; W2 = in[18]; N = FF; ndb = 176; gain = in[16]; WT = (bf16_t*)(ws + WS_W2GU); nts = true; }
;     else { r -= 5632; W = in[19]; K = FF; WT = (bf16_t*)(ws + WS_W2D); }
;     ...
;     constexpr int KL = TR_ORDER, DL = 3 - TR_ORDER;
;     const int rh = r >> 3, rl = r & 7, nq = ndb >> DL, kbh = rh / nq, dbh = rh - kbh * nq;
;     const int kb = (kbh << KL) + (rl >> DL), db = (dbh << DL) + (rl & ((1 << DL) - 1)), d0 = db * 64, k0 = kb * 64;
;     ...
;     const int kb = r / ndb, db = r - kb * ndb, d0 = db * 64, k0 = kb * 64;
;     ...
;     const int blk = d0 + 32 * ((lane & 15) >> 3);
;     const float* src = W; int s0 = blk;
;     if (kind == 1) { const int pn = blk >> 8, bj = (blk >> 7) & 1, o = blk & 127; src = bj ? W2 : W; s0 = pn * 128 + o; }
;     else if (kind == 2) s0 = win_src(blk);
;     TrItem t; t.src = src + (size_t)(k0 + (lane >> 4)) * N + s0 + 4 * (lane & 7); t.gain = gain ? gain + k0 + 8 * (lane & 7) : nullptr;
;     t.dst = WT + (size_t)(d0 + (lane >> 3)) * K + k0 + 8 * (lane & 7); t.N = N; t.K = K; t.nts = nts && TR_NTS;
;     if (woh) { t.dst = WT + ((size_t)((k0 >> 9) * 2048 + d0 + (lane >> 3))) * 512 + (k0 & 511) + 8 * (lane & 7); t.K = 512; }
;     return t;
; }
;     __device__ __forceinline__ int count() const { return (e0 - b0) + (e1 - b1) + (e2 - b2); }
; __device__ __forceinline__ void tr_all(const float* const* in, unsigned char* ws, LAS float* scr, int gw, int ngw, int lane, const TrRanges rg) {
;     const int TR_CNT = rg.count();
;     if (gw >= TR_CNT) return;
;     TrItem cur = tr_decode(rg.item(gw), in, ws, lane);
;     f32x4 v[16];
; #pragma unroll
;     for (int i = 0; i < 16; ++i) v[i] = TR_LOAD((const f32x4*)(cur.src + (size_t)(4 * i) * cur.N));
;     for (int it = gw; it < TR_CNT; it += ngw) {
;         const int nit = it + ngw; const bool hn = nit < TR_CNT;
;         TrItem nx = cur; f32x4 w[16];
;         if (hn) { nx = tr_decode(rg.item(nit), in, ws, lane);
; #pragma unroll
;             for (int i = 0; i < 16; ++i) w[i] = TR_LOAD((const f32x4*)(nx.src + (size_t)(4 * i) * nx.N)); }
;         LAS float* wp = scr + (lane >> 4) * 65 + 4 * (lane & 15);
; #pragma unroll
.Lseam_cv_1_1:
	s_cmp_gt_u32 s98, 7
	s_cbranch_scc1 .LBB0_570
	s_mov_b64 exec, -1
	s_lshl_b32 s99, s87, 1
	s_add_i32 s99, s99, s98
	s_add_i32 s99, s99, 0x1fa
	s_lshr_b32 s100, s99, 3
	s_lshr_b32 s101, s100, 3
	s_and_b32 s100, s100, 7
	s_and_b32 vcc_lo, s99, 7
	s_lshr_b32 vcc_hi, vcc_lo, 2
	s_lshl_b32 s101, s101, 1
	s_add_i32 s101, s101, vcc_hi
	s_and_b32 vcc_lo, vcc_lo, 3
	s_lshl_b32 s100, s100, 2
	s_add_i32 s100, s100, vcc_lo
	s_lshl_b32 s101, s101, 6
	s_lshl_b32 s100, s100, 6
	v_and_b32_e32 v66, 63, v1
	v_lshrrev_b32_e32 v67, 4, v66
	v_and_b32_e32 v68, 15, v66
	v_and_b32_e32 v73, 7, v66
	v_lshrrev_b32_e32 v72, 3, v66
	s_mul_i32 s99, s98, 0x4100
	v_mul_u32_u24_e32 v70, 0x104, v67
	v_lshl_add_u32 v70, v68, 4, v70
	v_add_u32_e32 v70, s99, v70
	v_mul_u32_u24_e32 v71, 0x820, v73
	v_lshl_add_u32 v71, v72, 2, v71
	v_add_u32_e32 v71, s99, v71
	s_lshl_b32 s99, s101, 13
	s_lshl_b32 vcc_lo, s100, 2
	s_add_i32 s99, s99, vcc_lo
	v_lshlrev_b32_e32 v69, 13, v67
	v_lshl_add_u32 v69, v68, 4, v69
	v_add_u32_e32 v69, s99, v69
	s_lshr_b32 s99, s101, 9
	s_lshl_b32 s99, s99, 21
	s_lshl_b32 vcc_lo, s100, 10
	s_add_i32 s99, s99, vcc_lo
	s_and_b32 vcc_lo, s101, 0x1ff
	s_lshl_b32 vcc_lo, vcc_lo, 1
	s_add_i32 s99, s99, vcc_lo
	v_lshlrev_b32_e32 v72, 10, v72
	v_lshl_add_u32 v72, v73, 4, v72
	v_add_u32_e32 v72, s99, v72
	v_readlane_b32 s100, v254, 32
	v_readlane_b32 s101, v254, 33
	s_nop 4
	global_load_dwordx4 v[2:5], v69, s[100:101] nt
	v_add_u32_e32 v68, 0x8000, v69
	global_load_dwordx4 v[6:9], v68, s[100:101] nt
	v_add_u32_e32 v67, 0x10000, v69
	global_load_dwordx4 v[10:13], v67, s[100:101] nt
	v_add_u32_e32 v68, 0x18000, v69
	global_load_dwordx4 v[14:17], v68, s[100:101] nt
	v_add_u32_e32 v67, 0x20000, v69
	global_load_dwordx4 v[18:21], v67, s[100:101] nt
	v_add_u32_e32 v68, 0x28000, v69
	global_load_dwordx4 v[22:25], v68, s[100:101] nt
	v_add_u32_e32 v67, 0x30000, v69
	global_load_dwordx4 v[26:29], v67, s[100:101] nt
	v_add_u32_e32 v68, 0x38000, v69
	global_load_dwordx4 v[30:33], v68, s[100:101] nt
	v_add_u32_e32 v67, 0x40000, v69
	global_load_dwordx4 v[34:37], v67, s[100:101] nt
	v_add_u32_e32 v68, 0x48000, v69
	global_load_dwordx4 v[38:41], v68, s[100:101] nt
	v_add_u32_e32 v67, 0x50000, v69
	global_load_dwordx4 v[42:45], v67, s[100:101] nt
	v_add_u32_e32 v68, 0x58000, v69
	global_load_dwordx4 v[46:49], v68, s[100:101] nt
	v_add_u32_e32 v67, 0x60000, v69
	global_load_dwordx4 v[50:53], v67, s[100:101] nt
	v_add_u32_e32 v68, 0x68000, v69
	global_load_dwordx4 v[54:57], v68, s[100:101] nt
	v_add_u32_e32 v67, 0x70000, v69
	global_load_dwordx4 v[58:61], v67, s[100:101] nt
	v_add_u32_e32 v68, 0x78000, v69
	global_load_dwordx4 v[62:65], v68, s[100:101] nt
	s_waitcnt vmcnt(15)
	ds_write_b32 v70, v2
	ds_write_b32 v70, v3 offset:4
	ds_write_b32 v70, v4 offset:8
	ds_write_b32 v70, v5 offset:12
	s_waitcnt vmcnt(14)
	ds_write_b32 v70, v6 offset:1040
	ds_write_b32 v70, v7 offset:1044
	ds_write_b32 v70, v8 offset:1048
	ds_write_b32 v70, v9 offset:1052
	s_waitcnt vmcnt(13)
	ds_write_b32 v70, v10 offset:2080
	ds_write_b32 v70, v11 offset:2084
	ds_write_b32 v70, v12 offset:2088
	ds_write_b32 v70, v13 offset:2092
	s_waitcnt vmcnt(12)
	ds_write_b32 v70, v14 offset:3120
	ds_write_b32 v70, v15 offset:3124
	ds_write_b32 v70, v16 offset:3128
	ds_write_b32 v70, v17 offset:3132
	s_waitcnt vmcnt(11)
	ds_write_b32 v70, v18 offset:4160
	ds_write_b32 v70, v19 offset:4164
	ds_write_b32 v70, v20 offset:4168
	ds_write_b32 v70, v21 offset:4172
	s_waitcnt vmcnt(10)
	ds_write_b32 v70, v22 offset:5200
	ds_write_b32 v70, v23 offset:5204
	ds_write_b32 v70, v24 offset:5208
	ds_write_b32 v70, v25 offset:5212
	s_waitcnt vmcnt(9)
	ds_write_b32 v70, v26 offset:6240
	ds_write_b32 v70, v27 offset:6244
	ds_write_b32 v70, v28 offset:6248
	ds_write_b32 v70, v29 offset:6252
	s_waitcnt vmcnt(8)
	ds_write_b32 v70, v30 offset:7280
	ds_write_b32 v70, v31 offset:7284
	ds_write_b32 v70, v32 offset:7288
	ds_write_b32 v70, v33 offset:7292
	s_waitcnt vmcnt(7)
	ds_write_b32 v70, v34 offset:8320
	ds_write_b32 v70, v35 offset:8324
	ds_write_b32 v70, v36 offset:8328
	ds_write_b32 v70, v37 offset:8332
	s_waitcnt vmcnt(6)
	ds_write_b32 v70, v38 offset:9360
	ds_write_b32 v70, v39 offset:9364
	ds_write_b32 v70, v40 offset:9368
	ds_write_b32 v70, v41 offset:9372
	s_waitcnt vmcnt(5)
	ds_write_b32 v70, v42 offset:10400
	ds_write_b32 v70, v43 offset:10404
	ds_write_b32 v70, v44 offset:10408
	ds_write_b32 v70, v45 offset:10412
	s_waitcnt vmcnt(4)
	ds_write_b32 v70, v46 offset:11440
	ds_write_b32 v70, v47 offset:11444
	ds_write_b32 v70, v48 offset:11448
	ds_write_b32 v70, v49 offset:11452
	s_waitcnt vmcnt(3)
; #define LAS __attribute__((address_space(3)))
; __device__ __forceinline__ unsigned cvtpk(float lo, float hi) { f32x2_t v = {lo, hi}; bf16x2_t b = __builtin_convertvector(v, bf16x2_t); return __builtin_bit_cast(unsigned, b); }
; __device__ __forceinline__ void tr_all(const float* const* in, unsigned char* ws, LAS float* scr, int gw, int ngw, int lane, const TrRanges rg) {
;     ...
;         asm volatile("s_waitcnt lgkmcnt(0)" ::: "memory");
;         const LAS float* rp = scr + (8 * (lane & 7)) * 65 + (lane >> 3);
; #pragma unroll
;         for (int j = 0; j < 8; ++j) { const LAS float* s = rp + 8 * j;
;             u32x4 o; o.x = cvtpk(s[0 * 65] * g0[0], s[1 * 65] * g0[1]); o.y = cvtpk(s[2 * 65] * g0[2], s[3 * 65] * g0[3]);
;             o.z = cvtpk(s[4 * 65] * g1[0], s[5 * 65] * g1[1]); o.w = cvtpk(s[6 * 65] * g1[2], s[7 * 65] * g1[3]);
;             if (cur.nts) __builtin_nontemporal_store(o, (u32x4*)(cur.dst + (size_t)(8 * j) * cur.K)); else *(u32x4*)(cur.dst + (size_t)(8 * j) * cur.K) = o; }
	ds_write_b32 v70, v50 offset:12480
	ds_write_b32 v70, v51 offset:12484
	ds_write_b32 v70, v52 offset:12488
	ds_write_b32 v70, v53 offset:12492
	s_waitcnt vmcnt(2)
	ds_write_b32 v70, v54 offset:13520
	ds_write_b32 v70, v55 offset:13524
	ds_write_b32 v70, v56 offset:13528
	ds_write_b32 v70, v57 offset:13532
	s_waitcnt vmcnt(1)
	ds_write_b32 v70, v58 offset:14560
	ds_write_b32 v70, v59 offset:14564
	ds_write_b32 v70, v60 offset:14568
	ds_write_b32 v70, v61 offset:14572
	s_waitcnt vmcnt(0)
	ds_write_b32 v70, v62 offset:15600
	ds_write_b32 v70, v63 offset:15604
	ds_write_b32 v70, v64 offset:15608
	ds_write_b32 v70, v65 offset:15612
	s_add_u32 s100, s84, 0x8700000
	s_addc_u32 s101, s85, 0
	s_waitcnt lgkmcnt(0)
	ds_read_b32 v2, v71
	ds_read_b32 v3, v71 offset:260
	ds_read_b32 v4, v71 offset:520
	ds_read_b32 v5, v71 offset:780
	ds_read_b32 v6, v71 offset:1040
	ds_read_b32 v7, v71 offset:1300
	ds_read_b32 v8, v71 offset:1560
	ds_read_b32 v9, v71 offset:1820
	ds_read_b32 v10, v71 offset:32
	ds_read_b32 v11, v71 offset:292
	ds_read_b32 v12, v71 offset:552
	ds_read_b32 v13, v71 offset:812
	ds_read_b32 v14, v71 offset:1072
	ds_read_b32 v15, v71 offset:1332
	ds_read_b32 v16, v71 offset:1592
	ds_read_b32 v17, v71 offset:1852
	ds_read_b32 v18, v71 offset:64
	ds_read_b32 v19, v71 offset:324
	ds_read_b32 v20, v71 offset:584
	ds_read_b32 v21, v71 offset:844
	ds_read_b32 v22, v71 offset:1104
	ds_read_b32 v23, v71 offset:1364
	ds_read_b32 v24, v71 offset:1624
	ds_read_b32 v25, v71 offset:1884
	ds_read_b32 v26, v71 offset:96
	ds_read_b32 v27, v71 offset:356
	ds_read_b32 v28, v71 offset:616
	ds_read_b32 v29, v71 offset:876
	ds_read_b32 v30, v71 offset:1136
	ds_read_b32 v31, v71 offset:1396
	ds_read_b32 v32, v71 offset:1656
	ds_read_b32 v33, v71 offset:1916
	ds_read_b32 v34, v71 offset:128
	ds_read_b32 v35, v71 offset:388
	ds_read_b32 v36, v71 offset:648
	ds_read_b32 v37, v71 offset:908
	ds_read_b32 v38, v71 offset:1168
	ds_read_b32 v39, v71 offset:1428
	ds_read_b32 v40, v71 offset:1688
	ds_read_b32 v41, v71 offset:1948
	ds_read_b32 v42, v71 offset:160
	ds_read_b32 v43, v71 offset:420
	ds_read_b32 v44, v71 offset:680
	ds_read_b32 v45, v71 offset:940
	ds_read_b32 v46, v71 offset:1200
	ds_read_b32 v47, v71 offset:1460
	ds_read_b32 v48, v71 offset:1720
	ds_read_b32 v49, v71 offset:1980
	ds_read_b32 v50, v71 offset:192
	ds_read_b32 v51, v71 offset:452
	ds_read_b32 v52, v71 offset:712
	ds_read_b32 v53, v71 offset:972
	ds_read_b32 v54, v71 offset:1232
	ds_read_b32 v55, v71 offset:1492
	ds_read_b32 v56, v71 offset:1752
	ds_read_b32 v57, v71 offset:2012
	ds_read_b32 v58, v71 offset:224
	ds_read_b32 v59, v71 offset:484
	ds_read_b32 v60, v71 offset:744
	ds_read_b32 v61, v71 offset:1004
	ds_read_b32 v62, v71 offset:1264
	ds_read_b32 v63, v71 offset:1524
	ds_read_b32 v64, v71 offset:1784
	ds_read_b32 v65, v71 offset:2044
	s_waitcnt lgkmcnt(15)
	v_cvt_pk_bf16_f32 v192, v2, v3
	v_cvt_pk_bf16_f32 v193, v4, v5
	v_cvt_pk_bf16_f32 v194, v6, v7
	v_cvt_pk_bf16_f32 v195, v8, v9
	global_store_dwordx4 v72, v[192:195], s[100:101]
	s_waitcnt lgkmcnt(15)
	v_cvt_pk_bf16_f32 v196, v10, v11
	v_cvt_pk_bf16_f32 v197, v12, v13
	v_cvt_pk_bf16_f32 v198, v14, v15
	v_cvt_pk_bf16_f32 v199, v16, v17
	v_add_u32_e32 v68, 0x2000, v72
	global_store_dwordx4 v68, v[196:199], s[100:101]
	s_waitcnt lgkmcnt(15)
	v_cvt_pk_bf16_f32 v200, v18, v19
	v_cvt_pk_bf16_f32 v201, v20, v21
	v_cvt_pk_bf16_f32 v202, v22, v23
	v_cvt_pk_bf16_f32 v203, v24, v25
	v_add_u32_e32 v67, 0x4000, v72
	global_store_dwordx4 v67, v[200:203], s[100:101]
	s_waitcnt lgkmcnt(15)
	v_cvt_pk_bf16_f32 v204, v26, v27
	v_cvt_pk_bf16_f32 v205, v28, v29
	v_cvt_pk_bf16_f32 v206, v30, v31
	v_cvt_pk_bf16_f32 v207, v32, v33
	v_add_u32_e32 v68, 0x6000, v72
	global_store_dwordx4 v68, v[204:207], s[100:101]
	s_waitcnt lgkmcnt(15)
	v_cvt_pk_bf16_f32 v208, v34, v35
	v_cvt_pk_bf16_f32 v209, v36, v37
	v_cvt_pk_bf16_f32 v210, v38, v39
	v_cvt_pk_bf16_f32 v211, v40, v41
	v_add_u32_e32 v67, 0x8000, v72
	global_store_dwordx4 v67, v[208:211], s[100:101]
	s_waitcnt lgkmcnt(15)
	v_cvt_pk_bf16_f32 v212, v42, v43
	v_cvt_pk_bf16_f32 v213, v44, v45
	v_cvt_pk_bf16_f32 v214, v46, v47
	v_cvt_pk_bf16_f32 v215, v48, v49
	v_add_u32_e32 v68, 0xa000, v72
	global_store_dwordx4 v68, v[212:215], s[100:101]
	s_waitcnt lgkmcnt(8)
	v_cvt_pk_bf16_f32 v216, v50, v51
	v_cvt_pk_bf16_f32 v217, v52, v53
	v_cvt_pk_bf16_f32 v218, v54, v55
	v_cvt_pk_bf16_f32 v219, v56, v57
	v_add_u32_e32 v67, 0xc000, v72
	global_store_dwordx4 v67, v[216:219], s[100:101]
	s_waitcnt lgkmcnt(0)
	v_cvt_pk_bf16_f32 v220, v58, v59
	v_cvt_pk_bf16_f32 v221, v60, v61
	v_cvt_pk_bf16_f32 v222, v62, v63
	v_cvt_pk_bf16_f32 v223, v64, v65
	v_add_u32_e32 v68, 0xe000, v72
	global_store_dwordx4 v68, v[220:223], s[100:101]

; #define LAS __attribute__((address_space(3)))
; #define TR_LOAD(p) __builtin_nontemporal_load(p)
; __device__ __forceinline__ TrItem tr_decode(int it, const float* const* in, unsigned char* ws, int lane) {
;     ...
;     else if ((r -= 1024) < 5632) { kind = 1; W = in[17]; W2 = in[18]; N = FF; ndb = 176; gain = in[16]; WT = (bf16_t*)(ws + WS_W2GU); nts = true; }
;     else { r -= 5632; W = in[19]; K = FF; WT = (bf16_t*)(ws + WS_W2D); }
;     ...
;     constexpr int KL = TR_ORDER, DL = 3 - TR_ORDER;
;     const int rh = r >> 3, rl = r & 7, nq = ndb >> DL, kbh = rh / nq, dbh = rh - kbh * nq;
;     const int kb = (kbh << KL) + (rl >> DL), db = (dbh << DL) + (rl & ((1 << DL) - 1)), d0 = db * 64, k0 = kb * 64;
;     ...
;     const int kb = r / ndb, db = r - kb * ndb, d0 = db * 64, k0 = kb * 64;
;     ...
;     const int blk = d0 + 32 * ((lane & 15) >> 3);
;     const float* src = W; int s0 = blk;
;     if (kind == 1) { const int pn = blk >> 8, bj = (blk >> 7) & 1, o = blk & 127; src = bj ? W2 : W; s0 = pn * 128 + o; }
;     else if (kind == 2) s0 = win_src(blk);
;     TrItem t; t.src = src + (size_t)(k0 + (lane >> 4)) * N + s0 + 4 * (lane & 7); t.gain = gain ? gain + k0 + 8 * (lane & 7) : nullptr;
;     t.dst = WT + (size_t)(d0 + (lane >> 3)) * K + k0 + 8 * (lane & 7); t.N = N; t.K = K; t.nts = nts && TR_NTS;
;     if (woh) { t.dst = WT + ((size_t)((k0 >> 9) * 2048 + d0 + (lane >> 3))) * 512 + (k0 & 511) + 8 * (lane & 7); t.K = 512; }
;     return t;
; }
;     __device__ __forceinline__ int count() const { return (e0 - b0) + (e1 - b1) + (e2 - b2); }
; __device__ __forceinline__ void tr_all(const float* const* in, unsigned char* ws, LAS float* scr, int gw, int ngw, int lane, const TrRanges rg) {
;     const int TR_CNT = rg.count();
;     if (gw >= TR_CNT) return;
;     TrItem cur = tr_decode(rg.item(gw), in, ws, lane);
;     f32x4 v[16];
; #pragma unroll
;     for (int i = 0; i < 16; ++i) v[i] = TR_LOAD((const f32x4*)(cur.src + (size_t)(4 * i) * cur.N));
;     for (int it = gw; it < TR_CNT; it += ngw) {
;         const int nit = it + ngw; const bool hn = nit < TR_CNT;
;         TrItem nx = cur; f32x4 w[16];
;         if (hn) { nx = tr_decode(rg.item(nit), in, ws, lane);
; #pragma unroll
;             for (int i = 0; i < 16; ++i) w[i] = TR_LOAD((const f32x4*)(nx.src + (size_t)(4 * i) * nx.N)); }
;         LAS float* wp = scr + (lane >> 4) * 65 + 4 * (lane & 15);
; #pragma unroll
.Lseam_cv_2:
	s_cmp_lt_u32 s98, 2
	s_cbranch_scc1 .LBB0_681
	s_cmp_gt_u32 s98, 5
	s_cbranch_scc1 .Lseam_cv_2_1
	s_mov_b64 exec, -1
	s_lshl_b32 s99, s87, 2
	s_add_i32 s99, s99, s98
	s_add_i32 s99, s99, 0xdfe
	s_lshr_b32 s100, s99, 3
	s_mul_i32 s101, s100, 0x5d2
	s_lshr_b32 s101, s101, 16
	s_mul_i32 vcc_lo, s101, 44
	s_sub_i32 s100, s100, vcc_lo
	s_and_b32 vcc_lo, s99, 7
	s_lshr_b32 vcc_hi, vcc_lo, 2
	s_lshl_b32 s101, s101, 1
	s_add_i32 s101, s101, vcc_hi
	s_and_b32 vcc_lo, vcc_lo, 3
	s_lshl_b32 s100, s100, 2
	s_add_i32 s100, s100, vcc_lo
	s_lshl_b32 s101, s101, 6
	s_lshl_b32 s100, s100, 6
	v_and_b32_e32 v66, 63, v1
	v_lshrrev_b32_e32 v67, 4, v66
	v_and_b32_e32 v68, 15, v66
	v_and_b32_e32 v73, 7, v66
	v_lshrrev_b32_e32 v72, 3, v66
	s_mul_i32 s99, s98, 0x4100
	v_mul_u32_u24_e32 v70, 0x104, v67
	v_lshl_add_u32 v70, v68, 4, v70
	v_add_u32_e32 v70, s99, v70
	v_mul_u32_u24_e32 v71, 0x820, v73
	v_lshl_add_u32 v71, v72, 2, v71
	v_add_u32_e32 v71, s99, v71
	s_mul_i32 s99, s101, 0x1600
	s_lshr_b32 vcc_lo, s100, 8
	s_lshl_b32 vcc_lo, vcc_lo, 7
	s_add_i32 s99, s99, vcc_lo
	s_and_b32 vcc_lo, s100, 0x7f
	s_add_i32 s99, s99, vcc_lo
	s_lshl_b32 s99, s99, 2
	v_mul_u32_u24_e32 v69, 0x5800, v67
	v_lshl_add_u32 v69, v68, 4, v69
	v_add_u32_e32 v69, s99, v69
	s_lshl_b32 s99, s100, 12
	s_lshl_b32 vcc_lo, s101, 1
	s_add_i32 s99, s99, vcc_lo
	v_lshlrev_b32_e32 v72, 12, v72
	v_lshl_add_u32 v72, v73, 4, v72
	v_add_u32_e32 v72, s99, v72
	s_lshl_b32 s99, s101, 2
	v_lshlrev_b32_e32 v73, 5, v73
	v_add_u32_e32 v73, s99, v73
	s_nop 0
	s_bitcmp1_b32 s100, 7
	v_readlane_b32 s100, v254, 6
	v_readlane_b32 s101, v254, 7
	v_readlane_b32 s98, v254, 8
	v_readlane_b32 s99, v254, 9
	s_nop 3
	s_cselect_b32 s100, s98, s100
	s_cselect_b32 s101, s99, s101
	v_readlane_b32 s98, v254, 4
	v_readlane_b32 s99, v254, 5
	global_load_dwordx4 v[2:5], v69, s[100:101] nt
	v_add_u32_e32 v68, 0x16000, v69
	global_load_dwordx4 v[6:9], v68, s[100:101] nt
	v_add_u32_e32 v67, 0x2c000, v69
	global_load_dwordx4 v[10:13], v67, s[100:101] nt
	v_add_u32_e32 v68, 0x42000, v69
	global_load_dwordx4 v[14:17], v68, s[100:101] nt
	v_add_u32_e32 v67, 0x58000, v69
	global_load_dwordx4 v[18:21], v67, s[100:101] nt
	v_add_u32_e32 v68, 0x6e000, v69
	global_load_dwordx4 v[22:25], v68, s[100:101] nt
	v_add_u32_e32 v67, 0x84000, v69
	global_load_dwordx4 v[26:29], v67, s[100:101] nt
	v_add_u32_e32 v68, 0x9a000, v69
	global_load_dwordx4 v[30:33], v68, s[100:101] nt
	v_add_u32_e32 v67, 0xb0000, v69
	global_load_dwordx4 v[34:37], v67, s[100:101] nt
	v_add_u32_e32 v68, 0xc6000, v69
	global_load_dwordx4 v[38:41], v68, s[100:101] nt
	v_add_u32_e32 v67, 0xdc000, v69
	global_load_dwordx4 v[42:45], v67, s[100:101] nt
	v_add_u32_e32 v68, 0xf2000, v69
	global_load_dwordx4 v[46:49], v68, s[100:101] nt
	v_add_u32_e32 v67, 0x108000, v69
	global_load_dwordx4 v[50:53], v67, s[100:101] nt
	v_add_u32_e32 v68, 0x11e000, v69
	global_load_dwordx4 v[54:57], v68, s[100:101] nt
	v_add_u32_e32 v67, 0x134000, v69
	global_load_dwordx4 v[58:61], v67, s[100:101] nt
	v_add_u32_e32 v68, 0x14a000, v69
	global_load_dwordx4 v[62:65], v68, s[100:101] nt
	global_load_dwordx4 v[74:77], v73, s[98:99]
	global_load_dwordx4 v[78:81], v73, s[98:99] offset:16
	s_waitcnt vmcnt(17)
	ds_write_b32 v70, v2
	ds_write_b32 v70, v3 offset:4
	ds_write_b32 v70, v4 offset:8
	ds_write_b32 v70, v5 offset:12
	s_waitcnt vmcnt(16)
	ds_write_b32 v70, v6 offset:1040
	ds_write_b32 v70, v7 offset:1044
	ds_write_b32 v70, v8 offset:1048
	ds_write_b32 v70, v9 offset:1052
	s_waitcnt vmcnt(15)
	ds_write_b32 v70, v10 offset:2080
	ds_write_b32 v70, v11 offset:2084
	ds_write_b32 v70, v12 offset:2088
	ds_write_b32 v70, v13 offset:2092
	s_waitcnt vmcnt(14)
	ds_write_b32 v70, v14 offset:3120
	ds_write_b32 v70, v15 offset:3124
	ds_write_b32 v70, v16 offset:3128
	ds_write_b32 v70, v17 offset:3132
	s_waitcnt vmcnt(13)
	ds_write_b32 v70, v18 offset:4160
	ds_write_b32 v70, v19 offset:4164
	ds_write_b32 v70, v20 offset:4168
	ds_write_b32 v70, v21 offset:4172
	s_waitcnt vmcnt(12)
	ds_write_b32 v70, v22 offset:5200
	ds_write_b32 v70, v23 offset:5204
	ds_write_b32 v70, v24 offset:5208
	ds_write_b32 v70, v25 offset:5212
	s_waitcnt vmcnt(11)
	ds_write_b32 v70, v26 offset:6240
	ds_write_b32 v70, v27 offset:6244
	ds_write_b32 v70, v28 offset:6248
	ds_write_b32 v70, v29 offset:6252
	s_waitcnt vmcnt(10)
	ds_write_b32 v70, v30 offset:7280
	ds_write_b32 v70, v31 offset:7284
	ds_write_b32 v70, v32 offset:7288
	ds_write_b32 v70, v33 offset:7292
	s_waitcnt vmcnt(9)
	ds_write_b32 v70, v34 offset:8320
	ds_write_b32 v70, v35 offset:8324
	ds_write_b32 v70, v36 offset:8328
	ds_write_b32 v70, v37 offset:8332
	s_waitcnt vmcnt(8)
	ds_write_b32 v70, v38 offset:9360
	ds_write_b32 v70, v39 offset:9364
	ds_write_b32 v70, v40 offset:9368
	ds_write_b32 v70, v41 offset:9372
	s_waitcnt vmcnt(7)
	ds_write_b32 v70, v42 offset:10400
	ds_write_b32 v70, v43 offset:10404
	ds_write_b32 v70, v44 offset:10408
	ds_write_b32 v70, v45 offset:10412
	s_waitcnt vmcnt(6)
	ds_write_b32 v70, v46 offset:11440
	ds_write_b32 v70, v47 offset:11444
	ds_write_b32 v70, v48 offset:11448
	ds_write_b32 v70, v49 offset:11452
	s_waitcnt vmcnt(5)
	ds_write_b32 v70, v50 offset:12480
	ds_write_b32 v70, v51 offset:12484
	ds_write_b32 v70, v52 offset:12488
	ds_write_b32 v70, v53 offset:12492
	s_waitcnt vmcnt(4)
	ds_write_b32 v70, v54 offset:13520
	ds_write_b32 v70, v55 offset:13524
	ds_write_b32 v70, v56 offset:13528
	ds_write_b32 v70, v57 offset:13532
	s_waitcnt vmcnt(3)
	ds_write_b32 v70, v58 offset:14560
	ds_write_b32 v70, v59 offset:14564
	ds_write_b32 v70, v60 offset:14568
	ds_write_b32 v70, v61 offset:14572
	s_waitcnt vmcnt(2)
; #define LAS __attribute__((address_space(3)))
; __device__ __forceinline__ unsigned cvtpk(float lo, float hi) { f32x2_t v = {lo, hi}; bf16x2_t b = __builtin_convertvector(v, bf16x2_t); return __builtin_bit_cast(unsigned, b); }
; __device__ __forceinline__ void tr_all(const float* const* in, unsigned char* ws, LAS float* scr, int gw, int ngw, int lane, const TrRanges rg) {
;     ...
;         f32x4 g0 = {1.f, 1.f, 1.f, 1.f}, g1 = {1.f, 1.f, 1.f, 1.f};
;         if (cur.gain) { g0 = *(const f32x4*)cur.gain; g1 = *(const f32x4*)(cur.gain + 4); }
;         asm volatile("s_waitcnt lgkmcnt(0)" ::: "memory");
;         const LAS float* rp = scr + (8 * (lane & 7)) * 65 + (lane >> 3);
; #pragma unroll
;         for (int j = 0; j < 8; ++j) { const LAS float* s = rp + 8 * j;
;             u32x4 o; o.x = cvtpk(s[0 * 65] * g0[0], s[1 * 65] * g0[1]); o.y = cvtpk(s[2 * 65] * g0[2], s[3 * 65] * g0[3]);
;             o.z = cvtpk(s[4 * 65] * g1[0], s[5 * 65] * g1[1]); o.w = cvtpk(s[6 * 65] * g1[2], s[7 * 65] * g1[3]);
;             if (cur.nts) __builtin_nontemporal_store(o, (u32x4*)(cur.dst + (size_t)(8 * j) * cur.K)); else *(u32x4*)(cur.dst + (size_t)(8 * j) * cur.K) = o; }
	ds_write_b32 v70, v62 offset:15600
	ds_write_b32 v70, v63 offset:15604
	ds_write_b32 v70, v64 offset:15608
	ds_write_b32 v70, v65 offset:15612
	s_add_u32 s100, s84, 0x8f00000
	s_addc_u32 s101, s85, 0
	s_waitcnt vmcnt(0) lgkmcnt(0)
	ds_read_b32 v2, v71
	ds_read_b32 v3, v71 offset:260
	ds_read_b32 v4, v71 offset:520
	ds_read_b32 v5, v71 offset:780
	ds_read_b32 v6, v71 offset:1040
	ds_read_b32 v7, v71 offset:1300
	ds_read_b32 v8, v71 offset:1560
	ds_read_b32 v9, v71 offset:1820
	ds_read_b32 v10, v71 offset:32
	ds_read_b32 v11, v71 offset:292
	ds_read_b32 v12, v71 offset:552
	ds_read_b32 v13, v71 offset:812
	ds_read_b32 v14, v71 offset:1072
	ds_read_b32 v15, v71 offset:1332
	ds_read_b32 v16, v71 offset:1592
	ds_read_b32 v17, v71 offset:1852
	ds_read_b32 v18, v71 offset:64
	ds_read_b32 v19, v71 offset:324
	ds_read_b32 v20, v71 offset:584
	ds_read_b32 v21, v71 offset:844
	ds_read_b32 v22, v71 offset:1104
	ds_read_b32 v23, v71 offset:1364
	ds_read_b32 v24, v71 offset:1624
	ds_read_b32 v25, v71 offset:1884
	ds_read_b32 v26, v71 offset:96
	ds_read_b32 v27, v71 offset:356
	ds_read_b32 v28, v71 offset:616
	ds_read_b32 v29, v71 offset:876
	ds_read_b32 v30, v71 offset:1136
	ds_read_b32 v31, v71 offset:1396
	ds_read_b32 v32, v71 offset:1656
	ds_read_b32 v33, v71 offset:1916
	ds_read_b32 v34, v71 offset:128
	ds_read_b32 v35, v71 offset:388
	ds_read_b32 v36, v71 offset:648
	ds_read_b32 v37, v71 offset:908
	ds_read_b32 v38, v71 offset:1168
	ds_read_b32 v39, v71 offset:1428
	ds_read_b32 v40, v71 offset:1688
	ds_read_b32 v41, v71 offset:1948
	ds_read_b32 v42, v71 offset:160
	ds_read_b32 v43, v71 offset:420
	ds_read_b32 v44, v71 offset:680
	ds_read_b32 v45, v71 offset:940
	ds_read_b32 v46, v71 offset:1200
	ds_read_b32 v47, v71 offset:1460
	ds_read_b32 v48, v71 offset:1720
	ds_read_b32 v49, v71 offset:1980
	ds_read_b32 v50, v71 offset:192
	ds_read_b32 v51, v71 offset:452
	ds_read_b32 v52, v71 offset:712
	ds_read_b32 v53, v71 offset:972
	ds_read_b32 v54, v71 offset:1232
	ds_read_b32 v55, v71 offset:1492
	ds_read_b32 v56, v71 offset:1752
	ds_read_b32 v57, v71 offset:2012
	ds_read_b32 v58, v71 offset:224
	ds_read_b32 v59, v71 offset:484
	ds_read_b32 v60, v71 offset:744
	ds_read_b32 v61, v71 offset:1004
	ds_read_b32 v62, v71 offset:1264
	ds_read_b32 v63, v71 offset:1524
	ds_read_b32 v64, v71 offset:1784
	ds_read_b32 v65, v71 offset:2044
	s_waitcnt lgkmcnt(15)
	v_mul_f32_e32 v2, v2, v74
	v_mul_f32_e32 v3, v3, v75
	v_mul_f32_e32 v4, v4, v76
	v_mul_f32_e32 v5, v5, v77
	v_mul_f32_e32 v6, v6, v78
	v_mul_f32_e32 v7, v7, v79
	v_mul_f32_e32 v8, v8, v80
	v_mul_f32_e32 v9, v9, v81
	v_cvt_pk_bf16_f32 v192, v2, v3
	v_cvt_pk_bf16_f32 v193, v4, v5
	v_cvt_pk_bf16_f32 v194, v6, v7
	v_cvt_pk_bf16_f32 v195, v8, v9
	global_store_dwordx4 v72, v[192:195], s[100:101]
	s_waitcnt lgkmcnt(15)
	v_mul_f32_e32 v10, v10, v74
	v_mul_f32_e32 v11, v11, v75
	v_mul_f32_e32 v12, v12, v76
	v_mul_f32_e32 v13, v13, v77
	v_mul_f32_e32 v14, v14, v78
	v_mul_f32_e32 v15, v15, v79
	v_mul_f32_e32 v16, v16, v80
	v_mul_f32_e32 v17, v17, v81
	v_cvt_pk_bf16_f32 v196, v10, v11
	v_cvt_pk_bf16_f32 v197, v12, v13
	v_cvt_pk_bf16_f32 v198, v14, v15
	v_cvt_pk_bf16_f32 v199, v16, v17
	v_add_u32_e32 v68, 0x8000, v72
	global_store_dwordx4 v68, v[196:199], s[100:101]
	s_waitcnt lgkmcnt(15)
	v_mul_f32_e32 v18, v18, v74
	v_mul_f32_e32 v19, v19, v75
	v_mul_f32_e32 v20, v20, v76
	v_mul_f32_e32 v21, v21, v77
	v_mul_f32_e32 v22, v22, v78
	v_mul_f32_e32 v23, v23, v79
	v_mul_f32_e32 v24, v24, v80
	v_mul_f32_e32 v25, v25, v81
	v_cvt_pk_bf16_f32 v200, v18, v19
	v_cvt_pk_bf16_f32 v201, v20, v21
	v_cvt_pk_bf16_f32 v202, v22, v23
	v_cvt_pk_bf16_f32 v203, v24, v25
	v_add_u32_e32 v67, 0x10000, v72
	global_store_dwordx4 v67, v[200:203], s[100:101]
	s_waitcnt lgkmcnt(15)
	v_mul_f32_e32 v26, v26, v74
	v_mul_f32_e32 v27, v27, v75
	v_mul_f32_e32 v28, v28, v76
	v_mul_f32_e32 v29, v29, v77
	v_mul_f32_e32 v30, v30, v78
	v_mul_f32_e32 v31, v31, v79
	v_mul_f32_e32 v32, v32, v80
	v_mul_f32_e32 v33, v33, v81
	v_cvt_pk_bf16_f32 v204, v26, v27
	v_cvt_pk_bf16_f32 v205, v28, v29
	v_cvt_pk_bf16_f32 v206, v30, v31
	v_cvt_pk_bf16_f32 v207, v32, v33
	v_add_u32_e32 v68, 0x18000, v72
	global_store_dwordx4 v68, v[204:207], s[100:101]
	s_waitcnt lgkmcnt(15)
	v_mul_f32_e32 v34, v34, v74
	v_mul_f32_e32 v35, v35, v75
	v_mul_f32_e32 v36, v36, v76
	v_mul_f32_e32 v37, v37, v77
	v_mul_f32_e32 v38, v38, v78
	v_mul_f32_e32 v39, v39, v79
	v_mul_f32_e32 v40, v40, v80
	v_mul_f32_e32 v41, v41, v81
	v_cvt_pk_bf16_f32 v208, v34, v35
	v_cvt_pk_bf16_f32 v209, v36, v37
	v_cvt_pk_bf16_f32 v210, v38, v39
	v_cvt_pk_bf16_f32 v211, v40, v41
	v_add_u32_e32 v67, 0x20000, v72
	global_store_dwordx4 v67, v[208:211], s[100:101]
	s_waitcnt lgkmcnt(15)
	v_mul_f32_e32 v42, v42, v74
	v_mul_f32_e32 v43, v43, v75
	v_mul_f32_e32 v44, v44, v76
	v_mul_f32_e32 v45, v45, v77
	v_mul_f32_e32 v46, v46, v78
	v_mul_f32_e32 v47, v47, v79
	v_mul_f32_e32 v48, v48, v80
	v_mul_f32_e32 v49, v49, v81
	v_cvt_pk_bf16_f32 v212, v42, v43
	v_cvt_pk_bf16_f32 v213, v44, v45
	v_cvt_pk_bf16_f32 v214, v46, v47
	v_cvt_pk_bf16_f32 v215, v48, v49
	v_add_u32_e32 v68, 0x28000, v72
	global_store_dwordx4 v68, v[212:215], s[100:101]
	s_waitcnt lgkmcnt(8)
	v_mul_f32_e32 v50, v50, v74
	v_mul_f32_e32 v51, v51, v75
	v_mul_f32_e32 v52, v52, v76
	v_mul_f32_e32 v53, v53, v77
	v_mul_f32_e32 v54, v54, v78
	v_mul_f32_e32 v55, v55, v79
	v_mul_f32_e32 v56, v56, v80
	v_mul_f32_e32 v57, v57, v81
	v_cvt_pk_bf16_f32 v216, v50, v51
	v_cvt_pk_bf16_f32 v217, v52, v53
	v_cvt_pk_bf16_f32 v218, v54, v55
	v_cvt_pk_bf16_f32 v219, v56, v57
	v_add_u32_e32 v67, 0x30000, v72
	global_store_dwordx4 v67, v[216:219], s[100:101]
	s_waitcnt lgkmcnt(0)
	v_mul_f32_e32 v58, v58, v74
	v_mul_f32_e32 v59, v59, v75
	v_mul_f32_e32 v60, v60, v76
	v_mul_f32_e32 v61, v61, v77
	v_mul_f32_e32 v62, v62, v78
	v_mul_f32_e32 v63, v63, v79
	v_mul_f32_e32 v64, v64, v80
	v_mul_f32_e32 v65, v65, v81
	v_cvt_pk_bf16_f32 v220, v58, v59
	v_cvt_pk_bf16_f32 v221, v60, v61
	v_cvt_pk_bf16_f32 v222, v62, v63
	v_cvt_pk_bf16_f32 v223, v64, v65
	v_add_u32_e32 v68, 0x38000, v72
	global_store_dwordx4 v68, v[220:223], s[100:101]
	s_branch .LBB0_681

; #define LAS __attribute__((address_space(3)))
; #define TR_LOAD(p) __builtin_nontemporal_load(p)
; __device__ __forceinline__ TrItem tr_decode(int it, const float* const* in, unsigned char* ws, int lane) {
;     ...
;     else if ((r -= 1024) < 5632) { kind = 1; W = in[17]; W2 = in[18]; N = FF; ndb = 176; gain = in[16]; WT = (bf16_t*)(ws + WS_W2GU); nts = true; }
;     else { r -= 5632; W = in[19]; K = FF; WT = (bf16_t*)(ws + WS_W2D); }
;     ...
;     constexpr int KL = TR_ORDER, DL = 3 - TR_ORDER;
;     const int rh = r >> 3, rl = r & 7, nq = ndb >> DL, kbh = rh / nq, dbh = rh - kbh * nq;
;     const int kb = (kbh << KL) + (rl >> DL), db = (dbh << DL) + (rl & ((1 << DL) - 1)), d0 = db * 64, k0 = kb * 64;
;     ...
;     const int kb = r / ndb, db = r - kb * ndb, d0 = db * 64, k0 = kb * 64;
;     ...
;     const int blk = d0 + 32 * ((lane & 15) >> 3);
;     const float* src = W; int s0 = blk;
;     if (kind == 1) { const int pn = blk >> 8, bj = (blk >> 7) & 1, o = blk & 127; src = bj ? W2 : W; s0 = pn * 128 + o; }
;     else if (kind == 2) s0 = win_src(blk);
;     TrItem t; t.src = src + (size_t)(k0 + (lane >> 4)) * N + s0 + 4 * (lane & 7); t.gain = gain ? gain + k0 + 8 * (lane & 7) : nullptr;
;     t.dst = WT + (size_t)(d0 + (lane >> 3)) * K + k0 + 8 * (lane & 7); t.N = N; t.K = K; t.nts = nts && TR_NTS;
;     if (woh) { t.dst = WT + ((size_t)((k0 >> 9) * 2048 + d0 + (lane >> 3))) * 512 + (k0 & 511) + 8 * (lane & 7); t.K = 512; }
;     return t;
; }
;     __device__ __forceinline__ int count() const { return (e0 - b0) + (e1 - b1) + (e2 - b2); }
; __device__ __forceinline__ void tr_all(const float* const* in, unsigned char* ws, LAS float* scr, int gw, int ngw, int lane, const TrRanges rg) {
;     const int TR_CNT = rg.count();
;     if (gw >= TR_CNT) return;
;     TrItem cur = tr_decode(rg.item(gw), in, ws, lane);
;     f32x4 v[16];
; #pragma unroll
;     for (int i = 0; i < 16; ++i) v[i] = TR_LOAD((const f32x4*)(cur.src + (size_t)(4 * i) * cur.N));
;     for (int it = gw; it < TR_CNT; it += ngw) {
;         const int nit = it + ngw; const bool hn = nit < TR_CNT;
;         TrItem nx = cur; f32x4 w[16];
;         if (hn) { nx = tr_decode(rg.item(nit), in, ws, lane);
; #pragma unroll
;             for (int i = 0; i < 16; ++i) w[i] = TR_LOAD((const f32x4*)(nx.src + (size_t)(4 * i) * nx.N)); }
;         LAS float* wp = scr + (lane >> 4) * 65 + 4 * (lane & 15);
; #pragma unroll
.Lseam_cv_3:
	s_cmp_lt_u32 s98, 2
	s_cbranch_scc1 .LBB0_1006
	s_cmp_gt_u32 s98, 5
	s_cbranch_scc1 .LBB0_1006
	s_mov_b64 exec, -1
	s_lshl_b32 s99, s87, 2
	s_add_i32 s99, s99, s98
	s_add_i32 s99, s99, 0x11fe
	s_lshr_b32 s100, s99, 3
	s_mul_i32 s101, s100, 0x5d2
	s_lshr_b32 s101, s101, 16
	s_mul_i32 vcc_lo, s101, 44
	s_sub_i32 s100, s100, vcc_lo
	s_and_b32 vcc_lo, s99, 7
	s_lshr_b32 vcc_hi, vcc_lo, 2
	s_lshl_b32 s101, s101, 1
	s_add_i32 s101, s101, vcc_hi
	s_and_b32 vcc_lo, vcc_lo, 3
	s_lshl_b32 s100, s100, 2
	s_add_i32 s100, s100, vcc_lo
	s_lshl_b32 s101, s101, 6
	s_lshl_b32 s100, s100, 6
	v_and_b32_e32 v66, 63, v1
	v_lshrrev_b32_e32 v67, 4, v66
	v_and_b32_e32 v68, 15, v66
	v_and_b32_e32 v73, 7, v66
	v_lshrrev_b32_e32 v72, 3, v66
	s_mul_i32 s99, s98, 0x4100
	v_mul_u32_u24_e32 v70, 0x104, v67
	v_lshl_add_u32 v70, v68, 4, v70
	v_add_u32_e32 v70, s99, v70
	v_mul_u32_u24_e32 v71, 0x820, v73
	v_lshl_add_u32 v71, v72, 2, v71
	v_add_u32_e32 v71, s99, v71
	s_mul_i32 s99, s101, 0x1600
	s_lshr_b32 vcc_lo, s100, 8
	s_lshl_b32 vcc_lo, vcc_lo, 7
	s_add_i32 s99, s99, vcc_lo
	s_and_b32 vcc_lo, s100, 0x7f
	s_add_i32 s99, s99, vcc_lo
	s_lshl_b32 s99, s99, 2
	v_mul_u32_u24_e32 v69, 0x5800, v67
	v_lshl_add_u32 v69, v68, 4, v69
	v_add_u32_e32 v69, s99, v69
	s_lshl_b32 s99, s100, 12
	s_lshl_b32 vcc_lo, s101, 1
	s_add_i32 s99, s99, vcc_lo
	v_lshlrev_b32_e32 v72, 12, v72
	v_lshl_add_u32 v72, v73, 4, v72
	v_add_u32_e32 v72, s99, v72
	s_lshl_b32 s99, s101, 2
	v_lshlrev_b32_e32 v73, 5, v73
	v_add_u32_e32 v73, s99, v73
	s_nop 0
	s_bitcmp1_b32 s100, 7
	v_readlane_b32 s100, v254, 6
	v_readlane_b32 s101, v254, 7
	v_readlane_b32 s98, v254, 8
	v_readlane_b32 s99, v254, 9
	s_nop 3
	s_cselect_b32 s100, s98, s100
	s_cselect_b32 s101, s99, s101
	v_readlane_b32 s98, v254, 4
	v_readlane_b32 s99, v254, 5
	global_load_dwordx4 v[2:5], v69, s[100:101] nt
	v_add_u32_e32 v68, 0x16000, v69
	global_load_dwordx4 v[6:9], v68, s[100:101] nt
	v_add_u32_e32 v67, 0x2c000, v69
	global_load_dwordx4 v[10:13], v67, s[100:101] nt
	v_add_u32_e32 v68, 0x42000, v69
	global_load_dwordx4 v[14:17], v68, s[100:101] nt
	v_add_u32_e32 v67, 0x58000, v69
	global_load_dwordx4 v[18:21], v67, s[100:101] nt
	v_add_u32_e32 v68, 0x6e000, v69
	global_load_dwordx4 v[22:25], v68, s[100:101] nt
	v_add_u32_e32 v67, 0x84000, v69
	global_load_dwordx4 v[26:29], v67, s[100:101] nt
	v_add_u32_e32 v68, 0x9a000, v69
	global_load_dwordx4 v[30:33], v68, s[100:101] nt
	v_add_u32_e32 v67, 0xb0000, v69
	global_load_dwordx4 v[34:37], v67, s[100:101] nt
	v_add_u32_e32 v68, 0xc6000, v69
	global_load_dwordx4 v[38:41], v68, s[100:101] nt
	v_add_u32_e32 v67, 0xdc000, v69
	global_load_dwordx4 v[42:45], v67, s[100:101] nt
	v_add_u32_e32 v68, 0xf2000, v69
	global_load_dwordx4 v[46:49], v68, s[100:101] nt
	v_add_u32_e32 v67, 0x108000, v69
	global_load_dwordx4 v[50:53], v67, s[100:101] nt
	v_add_u32_e32 v68, 0x11e000, v69
	global_load_dwordx4 v[54:57], v68, s[100:101] nt
	v_add_u32_e32 v67, 0x134000, v69
	global_load_dwordx4 v[58:61], v67, s[100:101] nt
	v_add_u32_e32 v68, 0x14a000, v69
	global_load_dwordx4 v[62:65], v68, s[100:101] nt
	global_load_dwordx4 v[74:77], v73, s[98:99]
	global_load_dwordx4 v[78:81], v73, s[98:99] offset:16
	s_waitcnt vmcnt(17)
	ds_write_b32 v70, v2
	ds_write_b32 v70, v3 offset:4
	ds_write_b32 v70, v4 offset:8
	ds_write_b32 v70, v5 offset:12
	s_waitcnt vmcnt(16)
	ds_write_b32 v70, v6 offset:1040
	ds_write_b32 v70, v7 offset:1044
	ds_write_b32 v70, v8 offset:1048
	ds_write_b32 v70, v9 offset:1052
	s_waitcnt vmcnt(15)
	ds_write_b32 v70, v10 offset:2080
	ds_write_b32 v70, v11 offset:2084
	ds_write_b32 v70, v12 offset:2088
	ds_write_b32 v70, v13 offset:2092
	s_waitcnt vmcnt(14)
	ds_write_b32 v70, v14 offset:3120
	ds_write_b32 v70, v15 offset:3124
	ds_write_b32 v70, v16 offset:3128
	ds_write_b32 v70, v17 offset:3132
	s_waitcnt vmcnt(13)
	ds_write_b32 v70, v18 offset:4160
	ds_write_b32 v70, v19 offset:4164
	ds_write_b32 v70, v20 offset:4168
	ds_write_b32 v70, v21 offset:4172
	s_waitcnt vmcnt(12)
	ds_write_b32 v70, v22 offset:5200
	ds_write_b32 v70, v23 offset:5204
	ds_write_b32 v70, v24 offset:5208
	ds_write_b32 v70, v25 offset:5212
	s_waitcnt vmcnt(11)
	ds_write_b32 v70, v26 offset:6240
	ds_write_b32 v70, v27 offset:6244
	ds_write_b32 v70, v28 offset:6248
	ds_write_b32 v70, v29 offset:6252
	s_waitcnt vmcnt(10)
	ds_write_b32 v70, v30 offset:7280
	ds_write_b32 v70, v31 offset:7284
	ds_write_b32 v70, v32 offset:7288
	ds_write_b32 v70, v33 offset:7292
	s_waitcnt vmcnt(9)
	ds_write_b32 v70, v34 offset:8320
	ds_write_b32 v70, v35 offset:8324
	ds_write_b32 v70, v36 offset:8328
	ds_write_b32 v70, v37 offset:8332
	s_waitcnt vmcnt(8)
	ds_write_b32 v70, v38 offset:9360
	ds_write_b32 v70, v39 offset:9364
	ds_write_b32 v70, v40 offset:9368
	ds_write_b32 v70, v41 offset:9372
	s_waitcnt vmcnt(7)
	ds_write_b32 v70, v42 offset:10400
	ds_write_b32 v70, v43 offset:10404
	ds_write_b32 v70, v44 offset:10408
	ds_write_b32 v70, v45 offset:10412
	s_waitcnt vmcnt(6)
	ds_write_b32 v70, v46 offset:11440
	ds_write_b32 v70, v47 offset:11444
	ds_write_b32 v70, v48 offset:11448
	ds_write_b32 v70, v49 offset:11452
	s_waitcnt vmcnt(5)
	ds_write_b32 v70, v50 offset:12480
	ds_write_b32 v70, v51 offset:12484
	ds_write_b32 v70, v52 offset:12488
	ds_write_b32 v70, v53 offset:12492
	s_waitcnt vmcnt(4)
	ds_write_b32 v70, v54 offset:13520
	ds_write_b32 v70, v55 offset:13524
	ds_write_b32 v70, v56 offset:13528
	ds_write_b32 v70, v57 offset:13532
	s_waitcnt vmcnt(3)
	ds_write_b32 v70, v58 offset:14560
	ds_write_b32 v70, v59 offset:14564
	ds_write_b32 v70, v60 offset:14568
	ds_write_b32 v70, v61 offset:14572
	s_waitcnt vmcnt(2)
; #define LAS __attribute__((address_space(3)))
; __device__ __forceinline__ unsigned cvtpk(float lo, float hi) { f32x2_t v = {lo, hi}; bf16x2_t b = __builtin_convertvector(v, bf16x2_t); return __builtin_bit_cast(unsigned, b); }
; __device__ __forceinline__ void tr_all(const float* const* in, unsigned char* ws, LAS float* scr, int gw, int ngw, int lane, const TrRanges rg) {
;     ...
;         f32x4 g0 = {1.f, 1.f, 1.f, 1.f}, g1 = {1.f, 1.f, 1.f, 1.f};
;         if (cur.gain) { g0 = *(const f32x4*)cur.gain; g1 = *(const f32x4*)(cur.gain + 4); }
;         asm volatile("s_waitcnt lgkmcnt(0)" ::: "memory");
;         const LAS float* rp = scr + (8 * (lane & 7)) * 65 + (lane >> 3);
; #pragma unroll
;         for (int j = 0; j < 8; ++j) { const LAS float* s = rp + 8 * j;
;             u32x4 o; o.x = cvtpk(s[0 * 65] * g0[0], s[1 * 65] * g0[1]); o.y = cvtpk(s[2 * 65] * g0[2], s[3 * 65] * g0[3]);
;             o.z = cvtpk(s[4 * 65] * g1[0], s[5 * 65] * g1[1]); o.w = cvtpk(s[6 * 65] * g1[2], s[7 * 65] * g1[3]);
;             if (cur.nts) __builtin_nontemporal_store(o, (u32x4*)(cur.dst + (size_t)(8 * j) * cur.K)); else *(u32x4*)(cur.dst + (size_t)(8 * j) * cur.K) = o; }
	ds_write_b32 v70, v62 offset:15600
	ds_write_b32 v70, v63 offset:15604
	ds_write_b32 v70, v64 offset:15608
	ds_write_b32 v70, v65 offset:15612
	s_add_u32 s100, s84, 0x8f00000
	s_addc_u32 s101, s85, 0
	s_waitcnt vmcnt(0) lgkmcnt(0)
	ds_read_b32 v2, v71
	ds_read_b32 v3, v71 offset:260
	ds_read_b32 v4, v71 offset:520
	ds_read_b32 v5, v71 offset:780
	ds_read_b32 v6, v71 offset:1040
	ds_read_b32 v7, v71 offset:1300
	ds_read_b32 v8, v71 offset:1560
	ds_read_b32 v9, v71 offset:1820
	ds_read_b32 v10, v71 offset:32
	ds_read_b32 v11, v71 offset:292
	ds_read_b32 v12, v71 offset:552
	ds_read_b32 v13, v71 offset:812
	ds_read_b32 v14, v71 offset:1072
	ds_read_b32 v15, v71 offset:1332
	ds_read_b32 v16, v71 offset:1592
	ds_read_b32 v17, v71 offset:1852
	ds_read_b32 v18, v71 offset:64
	ds_read_b32 v19, v71 offset:324
	ds_read_b32 v20, v71 offset:584
	ds_read_b32 v21, v71 offset:844
	ds_read_b32 v22, v71 offset:1104
	ds_read_b32 v23, v71 offset:1364
	ds_read_b32 v24, v71 offset:1624
	ds_read_b32 v25, v71 offset:1884
	ds_read_b32 v26, v71 offset:96
	ds_read_b32 v27, v71 offset:356
	ds_read_b32 v28, v71 offset:616
	ds_read_b32 v29, v71 offset:876
	ds_read_b32 v30, v71 offset:1136
	ds_read_b32 v31, v71 offset:1396
	ds_read_b32 v32, v71 offset:1656
	ds_read_b32 v33, v71 offset:1916
	ds_read_b32 v34, v71 offset:128
	ds_read_b32 v35, v71 offset:388
	ds_read_b32 v36, v71 offset:648
	ds_read_b32 v37, v71 offset:908
	ds_read_b32 v38, v71 offset:1168
	ds_read_b32 v39, v71 offset:1428
	ds_read_b32 v40, v71 offset:1688
	ds_read_b32 v41, v71 offset:1948
	ds_read_b32 v42, v71 offset:160
	ds_read_b32 v43, v71 offset:420
	ds_read_b32 v44, v71 offset:680
	ds_read_b32 v45, v71 offset:940
	ds_read_b32 v46, v71 offset:1200
	ds_read_b32 v47, v71 offset:1460
	ds_read_b32 v48, v71 offset:1720
	ds_read_b32 v49, v71 offset:1980
	ds_read_b32 v50, v71 offset:192
	ds_read_b32 v51, v71 offset:452
	ds_read_b32 v52, v71 offset:712
	ds_read_b32 v53, v71 offset:972
	ds_read_b32 v54, v71 offset:1232
	ds_read_b32 v55, v71 offset:1492
	ds_read_b32 v56, v71 offset:1752
	ds_read_b32 v57, v71 offset:2012
	ds_read_b32 v58, v71 offset:224
	ds_read_b32 v59, v71 offset:484
	ds_read_b32 v60, v71 offset:744
	ds_read_b32 v61, v71 offset:1004
	ds_read_b32 v62, v71 offset:1264
	ds_read_b32 v63, v71 offset:1524
	ds_read_b32 v64, v71 offset:1784
	ds_read_b32 v65, v71 offset:2044
	s_waitcnt lgkmcnt(15)
	v_mul_f32_e32 v2, v2, v74
	v_mul_f32_e32 v3, v3, v75
	v_mul_f32_e32 v4, v4, v76
	v_mul_f32_e32 v5, v5, v77
	v_mul_f32_e32 v6, v6, v78
	v_mul_f32_e32 v7, v7, v79
	v_mul_f32_e32 v8, v8, v80
	v_mul_f32_e32 v9, v9, v81
	v_cvt_pk_bf16_f32 v192, v2, v3
	v_cvt_pk_bf16_f32 v193, v4, v5
	v_cvt_pk_bf16_f32 v194, v6, v7
	v_cvt_pk_bf16_f32 v195, v8, v9
	global_store_dwordx4 v72, v[192:195], s[100:101]
	s_waitcnt lgkmcnt(15)
	v_mul_f32_e32 v10, v10, v74
	v_mul_f32_e32 v11, v11, v75
	v_mul_f32_e32 v12, v12, v76
	v_mul_f32_e32 v13, v13, v77
	v_mul_f32_e32 v14, v14, v78
	v_mul_f32_e32 v15, v15, v79
	v_mul_f32_e32 v16, v16, v80
	v_mul_f32_e32 v17, v17, v81
	v_cvt_pk_bf16_f32 v196, v10, v11
	v_cvt_pk_bf16_f32 v197, v12, v13
	v_cvt_pk_bf16_f32 v198, v14, v15
	v_cvt_pk_bf16_f32 v199, v16, v17
	v_add_u32_e32 v68, 0x8000, v72
	global_store_dwordx4 v68, v[196:199], s[100:101]
	s_waitcnt lgkmcnt(15)
	v_mul_f32_e32 v18, v18, v74
	v_mul_f32_e32 v19, v19, v75
	v_mul_f32_e32 v20, v20, v76
	v_mul_f32_e32 v21, v21, v77
	v_mul_f32_e32 v22, v22, v78
	v_mul_f32_e32 v23, v23, v79
	v_mul_f32_e32 v24, v24, v80
	v_mul_f32_e32 v25, v25, v81
	v_cvt_pk_bf16_f32 v200, v18, v19
	v_cvt_pk_bf16_f32 v201, v20, v21
	v_cvt_pk_bf16_f32 v202, v22, v23
	v_cvt_pk_bf16_f32 v203, v24, v25
	v_add_u32_e32 v67, 0x10000, v72
	global_store_dwordx4 v67, v[200:203], s[100:101]
	s_waitcnt lgkmcnt(15)
	v_mul_f32_e32 v26, v26, v74
	v_mul_f32_e32 v27, v27, v75
	v_mul_f32_e32 v28, v28, v76
	v_mul_f32_e32 v29, v29, v77
	v_mul_f32_e32 v30, v30, v78
	v_mul_f32_e32 v31, v31, v79
	v_mul_f32_e32 v32, v32, v80
	v_mul_f32_e32 v33, v33, v81
	v_cvt_pk_bf16_f32 v204, v26, v27
	v_cvt_pk_bf16_f32 v205, v28, v29
	v_cvt_pk_bf16_f32 v206, v30, v31
	v_cvt_pk_bf16_f32 v207, v32, v33
	v_add_u32_e32 v68, 0x18000, v72
	global_store_dwordx4 v68, v[204:207], s[100:101]
	s_waitcnt lgkmcnt(15)
	v_mul_f32_e32 v34, v34, v74
	v_mul_f32_e32 v35, v35, v75
	v_mul_f32_e32 v36, v36, v76
	v_mul_f32_e32 v37, v37, v77
	v_mul_f32_e32 v38, v38, v78
	v_mul_f32_e32 v39, v39, v79
	v_mul_f32_e32 v40, v40, v80
	v_mul_f32_e32 v41, v41, v81
	v_cvt_pk_bf16_f32 v208, v34, v35
	v_cvt_pk_bf16_f32 v209, v36, v37
	v_cvt_pk_bf16_f32 v210, v38, v39
	v_cvt_pk_bf16_f32 v211, v40, v41
	v_add_u32_e32 v67, 0x20000, v72
	global_store_dwordx4 v67, v[208:211], s[100:101]
	s_waitcnt lgkmcnt(15)
	v_mul_f32_e32 v42, v42, v74
	v_mul_f32_e32 v43, v43, v75
	v_mul_f32_e32 v44, v44, v76
	v_mul_f32_e32 v45, v45, v77
	v_mul_f32_e32 v46, v46, v78
	v_mul_f32_e32 v47, v47, v79
	v_mul_f32_e32 v48, v48, v80
	v_mul_f32_e32 v49, v49, v81
	v_cvt_pk_bf16_f32 v212, v42, v43
	v_cvt_pk_bf16_f32 v213, v44, v45
	v_cvt_pk_bf16_f32 v214, v46, v47
	v_cvt_pk_bf16_f32 v215, v48, v49
	v_add_u32_e32 v68, 0x28000, v72
	global_store_dwordx4 v68, v[212:215], s[100:101]
	s_waitcnt lgkmcnt(8)
	v_mul_f32_e32 v50, v50, v74
	v_mul_f32_e32 v51, v51, v75
	v_mul_f32_e32 v52, v52, v76
	v_mul_f32_e32 v53, v53, v77
	v_mul_f32_e32 v54, v54, v78
	v_mul_f32_e32 v55, v55, v79
	v_mul_f32_e32 v56, v56, v80
	v_mul_f32_e32 v57, v57, v81
	v_cvt_pk_bf16_f32 v216, v50, v51
	v_cvt_pk_bf16_f32 v217, v52, v53
	v_cvt_pk_bf16_f32 v218, v54, v55
	v_cvt_pk_bf16_f32 v219, v56, v57
	v_add_u32_e32 v67, 0x30000, v72
	global_store_dwordx4 v67, v[216:219], s[100:101]
	s_waitcnt lgkmcnt(0)
	v_mul_f32_e32 v58, v58, v74
	v_mul_f32_e32 v59, v59, v75
	v_mul_f32_e32 v60, v60, v76
	v_mul_f32_e32 v61, v61, v77
	v_mul_f32_e32 v62, v62, v78
	v_mul_f32_e32 v63, v63, v79
	v_mul_f32_e32 v64, v64, v80
	v_mul_f32_e32 v65, v65, v81
	v_cvt_pk_bf16_f32 v220, v58, v59
	v_cvt_pk_bf16_f32 v221, v60, v61
	v_cvt_pk_bf16_f32 v222, v62, v63
	v_cvt_pk_bf16_f32 v223, v64, v65
	v_add_u32_e32 v68, 0x38000, v72
	global_store_dwordx4 v68, v[220:223], s[100:101]
